# GEMM K-loops: lgkmcnt waits of up to 3 following MFMA groups merged into one wait (fewer 4-byte wait instructions in the MFMA stream)
# baseline (speedup 1.0000x reference)
.Lnodef_B0_0:
	ds_read_b128 v[150:153], v255 offset:12288
	ds_read_b128 v[146:149], v253 offset:8192
	ds_read_b128 v[142:145], v255 offset:8192
	ds_read_b128 v[154:157], v253 offset:12288
	s_add_i32 s2, s35, -1
	s_cmp_lt_i32 s2, s30
	s_cselect_b64 s[14:15], -1, 0
	s_cmp_ge_i32 s2, s30
	s_waitcnt lgkmcnt(4)
	v_mfma_f32_16x16x32_bf16 v[122:125], v[158:161], v[126:129], v[122:125]
	v_mfma_f32_16x16x32_bf16 v[118:121], v[162:165], v[126:129], v[118:121]
	v_mfma_f32_16x16x32_bf16 v[114:117], v[166:169], v[126:129], v[114:117]
	ds_read_b128 v[126:129], v247
	s_waitcnt lgkmcnt(2)
	v_mfma_f32_16x16x32_bf16 v[110:113], v[158:161], v[130:133], v[110:113]
	v_mfma_f32_16x16x32_bf16 v[106:109], v[162:165], v[130:133], v[106:109]
	v_mfma_f32_16x16x32_bf16 v[102:105], v[166:169], v[130:133], v[102:105]
	s_waitcnt vmcnt(5)
	ds_write_b128 v238, v[26:29]
	ds_write_b128 v238, v[22:25] offset:8192
.LBB0_287:
	s_lshl_b32 s2, s44, 8
	s_ashr_i32 s3, s2, 31
	s_lshl_b64 s[4:5], s[2:3], 11
	s_lshl_b32 s2, s22, 6
	s_ashr_i32 s3, s2, 31
	s_add_u32 s20, s25, s4
	s_addc_u32 s21, s26, s5
	s_lshl_b64 s[12:13], s[2:3], 1
	s_add_u32 s20, s20, s12
	s_addc_u32 s21, s21, s13
	global_load_dwordx4 v[22:25], v237, s[20:21]
	global_load_dwordx4 v[26:29], v236, s[20:21]
	s_andn2_b64 vcc, exec, s[14:15]
	ds_read_b128 v[130:133], v245
	v_mfma_f32_16x16x32_bf16 v[98:101], v[158:161], v[134:137], v[98:101]
	v_mfma_f32_16x16x32_bf16 v[94:97], v[162:165], v[134:137], v[94:97]
	v_mfma_f32_16x16x32_bf16 v[90:93], v[166:169], v[134:137], v[90:93]
	ds_read_b128 v[134:137], v247 offset:4096
	v_mfma_f32_16x16x32_bf16 v[86:89], v[158:161], v[138:141], v[86:89]
	v_mfma_f32_16x16x32_bf16 v[82:85], v[162:165], v[138:141], v[82:85]
	v_mfma_f32_16x16x32_bf16 v[54:57], v[166:169], v[138:141], v[54:57]
	ds_read_b128 v[170:173], v243
	ds_read_b128 v[174:177], v241
	ds_read_b128 v[178:181], v243 offset:4096
	ds_read_b128 v[138:141], v245 offset:4096
	s_waitcnt lgkmcnt(9)
	v_mfma_f32_16x16x32_bf16 v[78:81], v[158:161], v[142:145], v[78:81]
	v_mfma_f32_16x16x32_bf16 v[74:77], v[162:165], v[142:145], v[74:77]
	v_mfma_f32_16x16x32_bf16 v[70:73], v[166:169], v[142:145], v[70:73]
	s_waitcnt vmcnt(5)
	ds_write_b128 v238, v[18:21] offset:16384
	ds_write_b128 v238, v[14:17] offset:24576
.LBB0_289:
	global_load_dwordx4 v[14:17], v235, s[20:21]
	global_load_dwordx4 v[18:21], v234, s[20:21]
	s_and_b64 vcc, exec, s[2:3]
	ds_read_b128 v[142:145], v247 offset:8192
	s_waitcnt lgkmcnt(4)
	v_mfma_f32_16x16x32_bf16 v[66:69], v[158:161], v[146:149], v[66:69]
	v_mfma_f32_16x16x32_bf16 v[62:65], v[162:165], v[146:149], v[62:65]
	v_mfma_f32_16x16x32_bf16 v[58:61], v[166:169], v[146:149], v[58:61]
	ds_read_b128 v[146:149], v245 offset:8192
	v_mfma_f32_16x16x32_bf16 v[50:53], v[158:161], v[150:153], v[50:53]
	v_mfma_f32_16x16x32_bf16 v[46:49], v[162:165], v[150:153], v[46:49]
	v_mfma_f32_16x16x32_bf16 v[42:45], v[166:169], v[150:153], v[42:45]
	s_waitcnt vmcnt(5)
	ds_write_b128 v238, v[10:13] offset:32768
	ds_write_b128 v238, v[6:9] offset:40960
.LBB0_291:
	s_mul_i32 s14, s43, 0xc0
	s_ashr_i32 s15, s14, 31
	s_lshl_b64 s[14:15], s[14:15], 11
	s_add_u32 s20, s27, s14
	s_addc_u32 s21, s28, s15
	s_add_u32 s12, s20, s12
	s_addc_u32 s13, s21, s13
	global_load_dwordx4 v[6:9], v237, s[12:13]
	global_load_dwordx4 v[10:13], v236, s[12:13]
	s_and_b64 vcc, exec, s[2:3]
	ds_read_b128 v[150:153], v247 offset:12288
	v_mfma_f32_16x16x32_bf16 v[38:41], v[158:161], v[154:157], v[38:41]
	v_mfma_f32_16x16x32_bf16 v[34:37], v[162:165], v[154:157], v[34:37]
	v_mfma_f32_16x16x32_bf16 v[30:33], v[166:169], v[154:157], v[30:33]
	ds_read_b128 v[154:157], v245 offset:12288
	s_waitcnt lgkmcnt(8)
	v_mfma_f32_16x16x32_bf16 v[122:125], v[170:173], v[126:129], v[122:125]
	v_mfma_f32_16x16x32_bf16 v[118:121], v[174:177], v[126:129], v[118:121]
	v_mfma_f32_16x16x32_bf16 v[114:117], v[178:181], v[126:129], v[114:117]
	v_mfma_f32_16x16x32_bf16 v[110:113], v[170:173], v[130:133], v[110:113]
	v_mfma_f32_16x16x32_bf16 v[106:109], v[174:177], v[130:133], v[106:109]
	v_mfma_f32_16x16x32_bf16 v[102:105], v[178:181], v[130:133], v[102:105]
	s_waitcnt vmcnt(6)
	ds_write_b128 v238, v[2:5] offset:49152
.LBB0_293:
	global_load_dwordx4 v[2:5], v235, s[12:13]
	v_mfma_f32_16x16x32_bf16 v[98:101], v[170:173], v[134:137], v[98:101]
	v_mfma_f32_16x16x32_bf16 v[94:97], v[174:177], v[134:137], v[94:97]
	v_mfma_f32_16x16x32_bf16 v[90:93], v[178:181], v[134:137], v[90:93]
	v_mfma_f32_16x16x32_bf16 v[86:89], v[170:173], v[138:141], v[86:89]
	v_mfma_f32_16x16x32_bf16 v[82:85], v[174:177], v[138:141], v[82:85]
	v_mfma_f32_16x16x32_bf16 v[54:57], v[178:181], v[138:141], v[54:57]
	s_add_i32 s46, s22, 1
	s_cmp_lg_u32 s46, 16
	s_cbranch_scc1 .LBB0_297
	s_add_i32 s24, s24, s11
	s_cmpk_gt_i32 s24, 0x5f
	s_cbranch_scc1 .LBB0_296
	s_ashr_i32 s3, s24, 31
	s_lshr_b32 s3, s3, 27
	s_add_i32 s3, s24, s3
	s_ashr_i32 s3, s3, 5
	s_mov_b32 s2, s10
	s_lshl_b32 s4, s3, 6
	s_lshl_b32 s5, s24, 1
	s_sub_i32 s4, s5, s4
	s_and_b32 s2, s2, 7
	s_and_b32 s4, s4, -8
	s_or_b32 s44, s2, s4
	s_lshl_b32 s3, s3, 2
	s_and_b32 s5, s24, 3
	s_lshl_b32 s2, s44, 8
	s_or_b32 s43, s3, s5
	s_ashr_i32 s3, s2, 31
	s_lshl_b64 s[4:5], s[2:3], 11
	s_mul_i32 s2, s43, 0xc0
	s_ashr_i32 s3, s2, 31
	s_lshl_b64 s[14:15], s[2:3], 11

.LBB0_297:
	s_waitcnt lgkmcnt(0)
	s_barrier
	ds_read_b128 v[158:161], v250
	ds_read_b128 v[162:165], v248
	ds_read_b128 v[166:169], v250 offset:4096
	ds_read_b128 v[126:129], v254
	ds_read_b128 v[130:133], v252
	ds_read_b128 v[134:137], v254 offset:4096
	ds_read_b128 v[138:141], v252 offset:4096
	v_mfma_f32_16x16x32_bf16 v[78:81], v[170:173], v[142:145], v[78:81]
	v_mfma_f32_16x16x32_bf16 v[74:77], v[174:177], v[142:145], v[74:77]
	v_mfma_f32_16x16x32_bf16 v[70:73], v[178:181], v[142:145], v[70:73]
	v_mfma_f32_16x16x32_bf16 v[66:69], v[170:173], v[146:149], v[66:69]
	v_mfma_f32_16x16x32_bf16 v[62:65], v[174:177], v[146:149], v[62:65]
	v_mfma_f32_16x16x32_bf16 v[58:61], v[178:181], v[146:149], v[58:61]
	v_mfma_f32_16x16x32_bf16 v[50:53], v[170:173], v[150:153], v[50:53]
	v_mfma_f32_16x16x32_bf16 v[46:49], v[174:177], v[150:153], v[46:49]
	v_mfma_f32_16x16x32_bf16 v[42:45], v[178:181], v[150:153], v[42:45]
	v_mfma_f32_16x16x32_bf16 v[38:41], v[170:173], v[154:157], v[38:41]
	v_mfma_f32_16x16x32_bf16 v[34:37], v[174:177], v[154:157], v[34:37]
	v_mfma_f32_16x16x32_bf16 v[30:33], v[178:181], v[154:157], v[30:33]
	ds_read_b128 v[150:153], v254 offset:12288
	ds_read_b128 v[146:149], v252 offset:8192
	ds_read_b128 v[142:145], v254 offset:8192
	ds_read_b128 v[154:157], v252 offset:12288
	s_cmp_lt_i32 s35, s30
	s_cselect_b64 s[20:21], -1, 0
	s_cmp_ge_i32 s35, s30
	s_cselect_b64 s[12:13], -1, 0
	s_and_b64 vcc, exec, s[12:13]
	s_waitcnt lgkmcnt(4)
	v_mfma_f32_16x16x32_bf16 v[122:125], v[158:161], v[126:129], v[122:125]
	v_mfma_f32_16x16x32_bf16 v[118:121], v[162:165], v[126:129], v[118:121]
	v_mfma_f32_16x16x32_bf16 v[114:117], v[166:169], v[126:129], v[114:117]
	ds_read_b128 v[126:129], v246
	s_waitcnt lgkmcnt(2)
	v_mfma_f32_16x16x32_bf16 v[110:113], v[158:161], v[130:133], v[110:113]
	v_mfma_f32_16x16x32_bf16 v[106:109], v[162:165], v[130:133], v[106:109]
	v_mfma_f32_16x16x32_bf16 v[102:105], v[166:169], v[130:133], v[102:105]
	s_waitcnt vmcnt(5)
	ds_write_b128 v239, v[22:25]
	ds_write_b128 v239, v[26:29] offset:8192
.LBB0_299:
	s_lshl_b32 s2, s46, 6
	s_ashr_i32 s3, s2, 31
	s_add_u32 s22, s25, s4
	s_addc_u32 s23, s26, s5
	s_lshl_b64 s[4:5], s[2:3], 1
	s_add_u32 s22, s22, s4
	s_addc_u32 s23, s23, s5
	global_load_dwordx4 v[26:29], v237, s[22:23]
	global_load_dwordx4 v[22:25], v236, s[22:23]
	s_andn2_b64 vcc, exec, s[20:21]
	ds_read_b128 v[130:133], v244
	v_mfma_f32_16x16x32_bf16 v[98:101], v[158:161], v[134:137], v[98:101]
	v_mfma_f32_16x16x32_bf16 v[94:97], v[162:165], v[134:137], v[94:97]
	v_mfma_f32_16x16x32_bf16 v[90:93], v[166:169], v[134:137], v[90:93]
	ds_read_b128 v[134:137], v246 offset:4096
	v_mfma_f32_16x16x32_bf16 v[86:89], v[158:161], v[138:141], v[86:89]
	v_mfma_f32_16x16x32_bf16 v[82:85], v[162:165], v[138:141], v[82:85]
	v_mfma_f32_16x16x32_bf16 v[54:57], v[166:169], v[138:141], v[54:57]
	ds_read_b128 v[170:173], v242
	ds_read_b128 v[174:177], v240
	ds_read_b128 v[178:181], v242 offset:4096
	ds_read_b128 v[138:141], v244 offset:4096
	s_waitcnt lgkmcnt(9)
	v_mfma_f32_16x16x32_bf16 v[78:81], v[158:161], v[142:145], v[78:81]
	v_mfma_f32_16x16x32_bf16 v[74:77], v[162:165], v[142:145], v[74:77]
	v_mfma_f32_16x16x32_bf16 v[70:73], v[166:169], v[142:145], v[70:73]
	s_waitcnt vmcnt(5)
	ds_write_b128 v239, v[14:17] offset:16384
	ds_write_b128 v239, v[18:21] offset:24576
.LBB0_301:
	global_load_dwordx4 v[18:21], v235, s[22:23]
	global_load_dwordx4 v[14:17], v234, s[22:23]
	s_and_b64 vcc, exec, s[2:3]
	ds_read_b128 v[142:145], v246 offset:8192
	s_waitcnt lgkmcnt(4)
	v_mfma_f32_16x16x32_bf16 v[66:69], v[158:161], v[146:149], v[66:69]
	v_mfma_f32_16x16x32_bf16 v[62:65], v[162:165], v[146:149], v[62:65]
	v_mfma_f32_16x16x32_bf16 v[58:61], v[166:169], v[146:149], v[58:61]
	ds_read_b128 v[146:149], v244 offset:8192
	v_mfma_f32_16x16x32_bf16 v[50:53], v[158:161], v[150:153], v[50:53]
	v_mfma_f32_16x16x32_bf16 v[46:49], v[162:165], v[150:153], v[46:49]
	v_mfma_f32_16x16x32_bf16 v[42:45], v[166:169], v[150:153], v[42:45]
	s_waitcnt vmcnt(5)
	ds_write_b128 v239, v[6:9] offset:32768
	ds_write_b128 v239, v[10:13] offset:40960
.LBB0_303:
	s_add_u32 s14, s27, s14
	s_addc_u32 s15, s28, s15
	s_add_u32 s4, s14, s4
	s_addc_u32 s5, s15, s5
	global_load_dwordx4 v[10:13], v237, s[4:5]
	global_load_dwordx4 v[6:9], v236, s[4:5]
	s_and_b64 vcc, exec, s[2:3]
	ds_read_b128 v[150:153], v246 offset:12288
	v_mfma_f32_16x16x32_bf16 v[38:41], v[158:161], v[154:157], v[38:41]
	v_mfma_f32_16x16x32_bf16 v[34:37], v[162:165], v[154:157], v[34:37]
	v_mfma_f32_16x16x32_bf16 v[30:33], v[166:169], v[154:157], v[30:33]
	ds_read_b128 v[154:157], v244 offset:12288
	s_waitcnt lgkmcnt(8)
	v_mfma_f32_16x16x32_bf16 v[122:125], v[170:173], v[126:129], v[122:125]
	v_mfma_f32_16x16x32_bf16 v[118:121], v[174:177], v[126:129], v[118:121]
	v_mfma_f32_16x16x32_bf16 v[114:117], v[178:181], v[126:129], v[114:117]
	v_mfma_f32_16x16x32_bf16 v[110:113], v[170:173], v[130:133], v[110:113]
	v_mfma_f32_16x16x32_bf16 v[106:109], v[174:177], v[130:133], v[106:109]
	v_mfma_f32_16x16x32_bf16 v[102:105], v[178:181], v[130:133], v[102:105]
	s_waitcnt vmcnt(6)
	ds_write_b128 v239, v[2:5] offset:49152
.LBB0_305:
	global_load_dwordx4 v[2:5], v235, s[4:5]
	v_mfma_f32_16x16x32_bf16 v[98:101], v[170:173], v[134:137], v[98:101]
	v_mfma_f32_16x16x32_bf16 v[94:97], v[174:177], v[134:137], v[94:97]
	v_mfma_f32_16x16x32_bf16 v[90:93], v[178:181], v[134:137], v[90:93]
	v_mfma_f32_16x16x32_bf16 v[86:89], v[170:173], v[138:141], v[86:89]
	v_mfma_f32_16x16x32_bf16 v[82:85], v[174:177], v[138:141], v[82:85]
	v_mfma_f32_16x16x32_bf16 v[54:57], v[178:181], v[138:141], v[54:57]
	s_add_i32 s22, s46, 1
	s_cmp_lg_u32 s22, 16
	s_cbranch_scc1 .LBB0_309
	s_add_i32 s24, s24, s11
	s_cmpk_gt_i32 s24, 0x5f
	s_cbranch_scc1 .LBB0_308
	s_ashr_i32 s3, s24, 31
	s_lshr_b32 s3, s3, 27
	s_add_i32 s3, s24, s3
	s_ashr_i32 s3, s3, 5
	s_mov_b32 s2, s10
	s_lshl_b32 s4, s3, 6
	s_lshl_b32 s5, s24, 1
	s_sub_i32 s4, s5, s4
	s_and_b32 s2, s2, 7
	s_and_b32 s4, s4, -8
	s_lshl_b32 s3, s3, 2
	s_and_b32 s5, s24, 3
	s_or_b32 s43, s3, s5
	s_or_b32 s44, s2, s4

.Lnodef_G0_1:
	ds_read_b128 v[186:189], v255 offset:12288
	ds_read_b128 v[182:185], v253 offset:8192
	ds_read_b128 v[178:181], v255 offset:8192
	ds_read_b128 v[190:193], v253 offset:12288
	s_add_i32 s2, s42, -1
	s_cmp_lt_i32 s2, s37
	s_cselect_b64 s[24:25], -1, 0
	s_cmp_ge_i32 s2, s37
	s_waitcnt lgkmcnt(4)
	v_mfma_f32_16x16x32_bf16 v[158:161], v[194:197], v[162:165], v[158:161]
	v_mfma_f32_16x16x32_bf16 v[154:157], v[198:201], v[162:165], v[154:157]
	v_mfma_f32_16x16x32_bf16 v[150:153], v[202:205], v[162:165], v[150:153]
	v_mfma_f32_16x16x32_bf16 v[146:149], v[206:209], v[162:165], v[146:149]
	ds_read_b128 v[162:165], v247
	s_waitcnt lgkmcnt(2)
	v_mfma_f32_16x16x32_bf16 v[142:145], v[194:197], v[166:169], v[142:145]
	v_mfma_f32_16x16x32_bf16 v[138:141], v[198:201], v[166:169], v[138:141]
	v_mfma_f32_16x16x32_bf16 v[134:137], v[202:205], v[166:169], v[134:137]
	v_mfma_f32_16x16x32_bf16 v[130:133], v[206:209], v[166:169], v[130:133]
	s_waitcnt vmcnt(6)
	ds_write_b128 v235, v[30:33]
	ds_write_b128 v235, v[26:29] offset:8192
.LBB0_962:
	s_lshl_b32 s6, s51, 8
	s_ashr_i32 s7, s6, 31
	s_lshl_b32 s2, s28, 6
	s_ashr_i32 s3, s2, 31
	s_lshl_b64 s[22:23], s[6:7], 11
	s_add_u32 s26, s31, s22
	s_addc_u32 s27, s33, s23
	s_lshl_b64 s[22:23], s[2:3], 1
	s_add_u32 s26, s26, s22
	s_addc_u32 s27, s27, s23
	global_load_dwordx4 v[30:33], v233, s[26:27]
	global_load_dwordx4 v[26:29], v234, s[26:27]
	s_andn2_b64 vcc, exec, s[24:25]
	ds_read_b128 v[166:169], v245
	v_mfma_f32_16x16x32_bf16 v[126:129], v[194:197], v[170:173], v[126:129]
	v_mfma_f32_16x16x32_bf16 v[122:125], v[198:201], v[170:173], v[122:125]
	v_mfma_f32_16x16x32_bf16 v[118:121], v[202:205], v[170:173], v[118:121]
	v_mfma_f32_16x16x32_bf16 v[114:117], v[206:209], v[170:173], v[114:117]
	ds_read_b128 v[170:173], v247 offset:4096
	v_mfma_f32_16x16x32_bf16 v[110:113], v[194:197], v[174:177], v[110:113]
	v_mfma_f32_16x16x32_bf16 v[106:109], v[198:201], v[174:177], v[106:109]
	v_mfma_f32_16x16x32_bf16 v[102:105], v[202:205], v[174:177], v[102:105]
	v_mfma_f32_16x16x32_bf16 v[82:85], v[206:209], v[174:177], v[82:85]
	ds_read_b128 v[210:213], v243
	ds_read_b128 v[214:217], v241
	ds_read_b128 v[218:221], v243 offset:4096
	ds_read_b128 v[222:225], v241 offset:4096
	ds_read_b128 v[174:177], v245 offset:4096
	s_waitcnt lgkmcnt(10)
	v_mfma_f32_16x16x32_bf16 v[98:101], v[194:197], v[178:181], v[98:101]
	v_mfma_f32_16x16x32_bf16 v[94:97], v[198:201], v[178:181], v[94:97]
	v_mfma_f32_16x16x32_bf16 v[90:93], v[202:205], v[178:181], v[90:93]
	v_mfma_f32_16x16x32_bf16 v[86:89], v[206:209], v[178:181], v[86:89]
	s_waitcnt vmcnt(6)
	ds_write_b128 v235, v[22:25] offset:16384
	ds_write_b128 v235, v[18:21] offset:24576
.LBB0_964:
	global_load_dwordx4 v[18:21], v232, s[26:27]
	global_load_dwordx4 v[22:25], v231, s[26:27]
	s_and_b64 vcc, exec, s[2:3]
	ds_read_b128 v[178:181], v247 offset:8192
	s_waitcnt lgkmcnt(4)
	v_mfma_f32_16x16x32_bf16 v[78:81], v[194:197], v[182:185], v[78:81]
	v_mfma_f32_16x16x32_bf16 v[74:77], v[198:201], v[182:185], v[74:77]
	v_mfma_f32_16x16x32_bf16 v[70:73], v[202:205], v[182:185], v[70:73]
	v_mfma_f32_16x16x32_bf16 v[66:69], v[206:209], v[182:185], v[66:69]
	ds_read_b128 v[182:185], v245 offset:8192
	v_mfma_f32_16x16x32_bf16 v[62:65], v[194:197], v[186:189], v[62:65]
	v_mfma_f32_16x16x32_bf16 v[58:61], v[198:201], v[186:189], v[58:61]
	v_mfma_f32_16x16x32_bf16 v[54:57], v[202:205], v[186:189], v[54:57]
	v_mfma_f32_16x16x32_bf16 v[50:53], v[206:209], v[186:189], v[50:53]
	s_waitcnt vmcnt(6)
	ds_write_b128 v235, v[14:17] offset:32768
	ds_write_b128 v235, v[10:13] offset:40960
.LBB0_966:
	s_lshl_b32 s24, s50, 8
	s_ashr_i32 s25, s24, 31
	s_lshl_b64 s[26:27], s[24:25], 11
	s_add_u32 s26, s34, s26
	s_addc_u32 s27, s35, s27
	s_add_u32 s22, s26, s22
	s_addc_u32 s23, s27, s23
	global_load_dwordx4 v[10:13], v234, s[22:23]
	global_load_dwordx4 v[14:17], v233, s[22:23]
	s_and_b64 vcc, exec, s[2:3]
	ds_read_b128 v[186:189], v247 offset:12288
	v_mfma_f32_16x16x32_bf16 v[46:49], v[194:197], v[190:193], v[46:49]
	v_mfma_f32_16x16x32_bf16 v[42:45], v[198:201], v[190:193], v[42:45]
	v_mfma_f32_16x16x32_bf16 v[38:41], v[202:205], v[190:193], v[38:41]
	v_mfma_f32_16x16x32_bf16 v[34:37], v[206:209], v[190:193], v[34:37]
	ds_read_b128 v[190:193], v245 offset:12288
	s_waitcnt lgkmcnt(8)
	v_mfma_f32_16x16x32_bf16 v[158:161], v[210:213], v[162:165], v[158:161]
	v_mfma_f32_16x16x32_bf16 v[154:157], v[214:217], v[162:165], v[154:157]
	v_mfma_f32_16x16x32_bf16 v[150:153], v[218:221], v[162:165], v[150:153]
	v_mfma_f32_16x16x32_bf16 v[146:149], v[222:225], v[162:165], v[146:149]
	v_mfma_f32_16x16x32_bf16 v[142:145], v[210:213], v[166:169], v[142:145]
	v_mfma_f32_16x16x32_bf16 v[138:141], v[214:217], v[166:169], v[138:141]
	v_mfma_f32_16x16x32_bf16 v[134:137], v[218:221], v[166:169], v[134:137]
	v_mfma_f32_16x16x32_bf16 v[130:133], v[222:225], v[166:169], v[130:133]
	s_waitcnt vmcnt(6)
	ds_write_b128 v235, v[6:9] offset:49152
	ds_write_b128 v235, v[2:5] offset:57344
.LBB0_968:
	global_load_dwordx4 v[2:5], v232, s[22:23]
	global_load_dwordx4 v[6:9], v231, s[22:23]
	v_mfma_f32_16x16x32_bf16 v[126:129], v[210:213], v[170:173], v[126:129]
	v_mfma_f32_16x16x32_bf16 v[122:125], v[214:217], v[170:173], v[122:125]
	v_mfma_f32_16x16x32_bf16 v[118:121], v[218:221], v[170:173], v[118:121]
	v_mfma_f32_16x16x32_bf16 v[114:117], v[222:225], v[170:173], v[114:117]
	v_mfma_f32_16x16x32_bf16 v[110:113], v[210:213], v[174:177], v[110:113]
	v_mfma_f32_16x16x32_bf16 v[106:109], v[214:217], v[174:177], v[106:109]
	v_mfma_f32_16x16x32_bf16 v[102:105], v[218:221], v[174:177], v[102:105]
	v_mfma_f32_16x16x32_bf16 v[82:85], v[222:225], v[174:177], v[82:85]
	s_lshl_b64 s[2:3], s[6:7], 10
	s_lshl_b64 s[22:23], s[24:25], 10
	s_add_i32 s53, s28, 1
	s_cmp_lg_u32 s53, 16
	s_cbranch_scc1 .LBB0_972
	s_add_i32 s30, s30, s11
	s_cmp_gt_i32 s30, 31
	s_cbranch_scc1 .LBB0_971
	s_ashr_i32 s3, s30, 31
	s_lshr_b32 s3, s3, 27
	s_add_i32 s3, s30, s3
	s_ashr_i32 s3, s3, 5
	s_mov_b32 s2, s10
	s_lshl_b32 s6, s3, 6
	s_lshl_b32 s7, s30, 1
	s_sub_i32 s6, s7, s6
	s_and_b32 s2, s2, 7
	s_and_b32 s6, s6, -8
	s_lshl_b32 s3, s3, 2
	s_and_b32 s7, s30, 3
	s_or_b32 s50, s3, s7
	s_or_b32 s51, s2, s6
	s_lshl_b32 s2, s51, 8
	s_lshl_b32 s6, s50, 8
	s_ashr_i32 s3, s2, 31
	s_ashr_i32 s7, s6, 31
	s_lshl_b64 s[2:3], s[2:3], 10
	s_lshl_b64 s[22:23], s[6:7], 10

.LBB0_972:
	s_waitcnt lgkmcnt(0)
	s_barrier
	ds_read_b128 v[194:197], v250
	ds_read_b128 v[198:201], v248
	ds_read_b128 v[202:205], v250 offset:4096
	ds_read_b128 v[206:209], v248 offset:4096
	ds_read_b128 v[162:165], v254
	ds_read_b128 v[166:169], v252
	ds_read_b128 v[170:173], v254 offset:4096
	ds_read_b128 v[174:177], v252 offset:4096
	v_mfma_f32_16x16x32_bf16 v[98:101], v[210:213], v[178:181], v[98:101]
	v_mfma_f32_16x16x32_bf16 v[94:97], v[214:217], v[178:181], v[94:97]
	v_mfma_f32_16x16x32_bf16 v[90:93], v[218:221], v[178:181], v[90:93]
	v_mfma_f32_16x16x32_bf16 v[86:89], v[222:225], v[178:181], v[86:89]
	v_mfma_f32_16x16x32_bf16 v[78:81], v[210:213], v[182:185], v[78:81]
	v_mfma_f32_16x16x32_bf16 v[74:77], v[214:217], v[182:185], v[74:77]
	v_mfma_f32_16x16x32_bf16 v[70:73], v[218:221], v[182:185], v[70:73]
	v_mfma_f32_16x16x32_bf16 v[66:69], v[222:225], v[182:185], v[66:69]
	v_mfma_f32_16x16x32_bf16 v[62:65], v[210:213], v[186:189], v[62:65]
	v_mfma_f32_16x16x32_bf16 v[58:61], v[214:217], v[186:189], v[58:61]
	v_mfma_f32_16x16x32_bf16 v[54:57], v[218:221], v[186:189], v[54:57]
	v_mfma_f32_16x16x32_bf16 v[50:53], v[222:225], v[186:189], v[50:53]
	v_mfma_f32_16x16x32_bf16 v[46:49], v[210:213], v[190:193], v[46:49]
	v_mfma_f32_16x16x32_bf16 v[42:45], v[214:217], v[190:193], v[42:45]
	v_mfma_f32_16x16x32_bf16 v[38:41], v[218:221], v[190:193], v[38:41]
	v_mfma_f32_16x16x32_bf16 v[34:37], v[222:225], v[190:193], v[34:37]
	ds_read_b128 v[186:189], v254 offset:12288
	ds_read_b128 v[182:185], v252 offset:8192
	ds_read_b128 v[178:181], v254 offset:8192
	ds_read_b128 v[190:193], v252 offset:12288
	s_cmp_lt_i32 s42, s37
	s_cselect_b64 s[26:27], -1, 0
	s_cmp_ge_i32 s42, s37
	s_cselect_b64 s[6:7], -1, 0
	s_and_b64 vcc, exec, s[6:7]
	s_waitcnt lgkmcnt(4)
	v_mfma_f32_16x16x32_bf16 v[158:161], v[194:197], v[162:165], v[158:161]
	v_mfma_f32_16x16x32_bf16 v[154:157], v[198:201], v[162:165], v[154:157]
	v_mfma_f32_16x16x32_bf16 v[150:153], v[202:205], v[162:165], v[150:153]
	v_mfma_f32_16x16x32_bf16 v[146:149], v[206:209], v[162:165], v[146:149]
	ds_read_b128 v[162:165], v246
	s_waitcnt lgkmcnt(2)
	v_mfma_f32_16x16x32_bf16 v[142:145], v[194:197], v[166:169], v[142:145]
	v_mfma_f32_16x16x32_bf16 v[138:141], v[198:201], v[166:169], v[138:141]
	v_mfma_f32_16x16x32_bf16 v[134:137], v[202:205], v[166:169], v[134:137]
	v_mfma_f32_16x16x32_bf16 v[130:133], v[206:209], v[166:169], v[130:133]
	s_waitcnt vmcnt(6)
	ds_write_b128 v236, v[26:29]
	ds_write_b128 v236, v[30:33] offset:8192
.LBB0_974:
	s_lshl_b32 s24, s53, 6
	s_ashr_i32 s25, s24, 31
	s_lshl_b64 s[2:3], s[2:3], 1
	s_add_u32 s2, s31, s2
	s_addc_u32 s3, s33, s3
	s_lshl_b64 s[24:25], s[24:25], 1
	s_add_u32 s28, s2, s24
	s_addc_u32 s29, s3, s25
	global_load_dwordx4 v[30:33], v234, s[28:29]
	global_load_dwordx4 v[26:29], v233, s[28:29]
	s_andn2_b64 vcc, exec, s[26:27]
	ds_read_b128 v[166:169], v244
	v_mfma_f32_16x16x32_bf16 v[126:129], v[194:197], v[170:173], v[126:129]
	v_mfma_f32_16x16x32_bf16 v[122:125], v[198:201], v[170:173], v[122:125]
	v_mfma_f32_16x16x32_bf16 v[118:121], v[202:205], v[170:173], v[118:121]
	v_mfma_f32_16x16x32_bf16 v[114:117], v[206:209], v[170:173], v[114:117]
	ds_read_b128 v[170:173], v246 offset:4096
	v_mfma_f32_16x16x32_bf16 v[110:113], v[194:197], v[174:177], v[110:113]
	v_mfma_f32_16x16x32_bf16 v[106:109], v[198:201], v[174:177], v[106:109]
	v_mfma_f32_16x16x32_bf16 v[102:105], v[202:205], v[174:177], v[102:105]
	v_mfma_f32_16x16x32_bf16 v[82:85], v[206:209], v[174:177], v[82:85]
	ds_read_b128 v[210:213], v242
	ds_read_b128 v[214:217], v237
	ds_read_b128 v[218:221], v242 offset:4096
	ds_read_b128 v[222:225], v237 offset:4096
	ds_read_b128 v[174:177], v244 offset:4096
	s_waitcnt lgkmcnt(10)
	v_mfma_f32_16x16x32_bf16 v[98:101], v[194:197], v[178:181], v[98:101]
	v_mfma_f32_16x16x32_bf16 v[94:97], v[198:201], v[178:181], v[94:97]
	v_mfma_f32_16x16x32_bf16 v[90:93], v[202:205], v[178:181], v[90:93]
	v_mfma_f32_16x16x32_bf16 v[86:89], v[206:209], v[178:181], v[86:89]
	s_waitcnt vmcnt(6)
	ds_write_b128 v236, v[18:21] offset:16384
	ds_write_b128 v236, v[22:25] offset:24576
.LBB0_976:
	global_load_dwordx4 v[22:25], v232, s[28:29]
	global_load_dwordx4 v[18:21], v231, s[28:29]
	s_and_b64 vcc, exec, s[2:3]
	ds_read_b128 v[178:181], v246 offset:8192
	s_waitcnt lgkmcnt(4)
	v_mfma_f32_16x16x32_bf16 v[78:81], v[194:197], v[182:185], v[78:81]
	v_mfma_f32_16x16x32_bf16 v[74:77], v[198:201], v[182:185], v[74:77]
	v_mfma_f32_16x16x32_bf16 v[70:73], v[202:205], v[182:185], v[70:73]
	v_mfma_f32_16x16x32_bf16 v[66:69], v[206:209], v[182:185], v[66:69]
	ds_read_b128 v[182:185], v244 offset:8192
	v_mfma_f32_16x16x32_bf16 v[62:65], v[194:197], v[186:189], v[62:65]
	v_mfma_f32_16x16x32_bf16 v[58:61], v[198:201], v[186:189], v[58:61]
	v_mfma_f32_16x16x32_bf16 v[54:57], v[202:205], v[186:189], v[54:57]
	v_mfma_f32_16x16x32_bf16 v[50:53], v[206:209], v[186:189], v[50:53]
	s_waitcnt vmcnt(6)
	ds_write_b128 v236, v[10:13] offset:32768
	ds_write_b128 v236, v[14:17] offset:40960
.LBB0_978:
	s_lshl_b64 s[22:23], s[22:23], 1
	s_add_u32 s22, s34, s22
	s_addc_u32 s23, s35, s23
	s_add_u32 s22, s22, s24
	s_addc_u32 s23, s23, s25
	global_load_dwordx4 v[14:17], v234, s[22:23]
	global_load_dwordx4 v[10:13], v233, s[22:23]
	s_and_b64 vcc, exec, s[2:3]
	ds_read_b128 v[186:189], v246 offset:12288
	v_mfma_f32_16x16x32_bf16 v[46:49], v[194:197], v[190:193], v[46:49]
	v_mfma_f32_16x16x32_bf16 v[42:45], v[198:201], v[190:193], v[42:45]
	v_mfma_f32_16x16x32_bf16 v[38:41], v[202:205], v[190:193], v[38:41]
	v_mfma_f32_16x16x32_bf16 v[34:37], v[206:209], v[190:193], v[34:37]
	ds_read_b128 v[190:193], v244 offset:12288
	s_waitcnt lgkmcnt(8)
	v_mfma_f32_16x16x32_bf16 v[158:161], v[210:213], v[162:165], v[158:161]
	v_mfma_f32_16x16x32_bf16 v[154:157], v[214:217], v[162:165], v[154:157]
	v_mfma_f32_16x16x32_bf16 v[150:153], v[218:221], v[162:165], v[150:153]
	v_mfma_f32_16x16x32_bf16 v[146:149], v[222:225], v[162:165], v[146:149]
	v_mfma_f32_16x16x32_bf16 v[142:145], v[210:213], v[166:169], v[142:145]
	v_mfma_f32_16x16x32_bf16 v[138:141], v[214:217], v[166:169], v[138:141]
	v_mfma_f32_16x16x32_bf16 v[134:137], v[218:221], v[166:169], v[134:137]
	v_mfma_f32_16x16x32_bf16 v[130:133], v[222:225], v[166:169], v[130:133]
	s_waitcnt vmcnt(6)
	ds_write_b128 v236, v[2:5] offset:49152
	ds_write_b128 v236, v[6:9] offset:57344
.LBB0_980:
	global_load_dwordx4 v[6:9], v232, s[22:23]
	global_load_dwordx4 v[2:5], v231, s[22:23]
	v_mfma_f32_16x16x32_bf16 v[126:129], v[210:213], v[170:173], v[126:129]
	v_mfma_f32_16x16x32_bf16 v[122:125], v[214:217], v[170:173], v[122:125]
	v_mfma_f32_16x16x32_bf16 v[118:121], v[218:221], v[170:173], v[118:121]
	v_mfma_f32_16x16x32_bf16 v[114:117], v[222:225], v[170:173], v[114:117]
	v_mfma_f32_16x16x32_bf16 v[110:113], v[210:213], v[174:177], v[110:113]
	v_mfma_f32_16x16x32_bf16 v[106:109], v[214:217], v[174:177], v[106:109]
	v_mfma_f32_16x16x32_bf16 v[102:105], v[218:221], v[174:177], v[102:105]
	v_mfma_f32_16x16x32_bf16 v[82:85], v[222:225], v[174:177], v[82:85]
	s_add_i32 s28, s53, 1
	s_cmp_lg_u32 s28, 16
	s_cbranch_scc1 .LBB0_984
	s_add_i32 s30, s30, s11
	s_cmp_gt_i32 s30, 31
	s_cbranch_scc1 .LBB0_983
	s_ashr_i32 s3, s30, 31
	s_lshr_b32 s3, s3, 27
	s_add_i32 s3, s30, s3
	s_ashr_i32 s3, s3, 5
	s_mov_b32 s2, s10
	s_lshl_b32 s22, s3, 6
	s_lshl_b32 s23, s30, 1
	s_sub_i32 s22, s23, s22
	s_and_b32 s2, s2, 7
	s_and_b32 s22, s22, -8
	s_lshl_b32 s3, s3, 2
	s_and_b32 s23, s30, 3
	s_or_b32 s50, s3, s23
	s_or_b32 s51, s2, s22

.Lnodef_I0_2:
	ds_read_b128 v[186:189], v255 offset:12288
	ds_read_b128 v[182:185], v253 offset:8192
	ds_read_b128 v[178:181], v255 offset:8192
	ds_read_b128 v[190:193], v253 offset:12288
	s_add_i32 s2, s41, -1
	s_cmp_lt_i32 s2, s40
	s_cselect_b64 s[14:15], -1, 0
	s_cmp_ge_i32 s2, s40
	s_waitcnt lgkmcnt(4)
	v_mfma_f32_16x16x32_bf16 v[158:161], v[194:197], v[162:165], v[158:161]
	v_mfma_f32_16x16x32_bf16 v[150:153], v[198:201], v[162:165], v[150:153]
	v_mfma_f32_16x16x32_bf16 v[154:157], v[202:205], v[162:165], v[154:157]
	v_mfma_f32_16x16x32_bf16 v[146:149], v[206:209], v[162:165], v[146:149]
	ds_read_b128 v[162:165], v247
	s_waitcnt lgkmcnt(2)
	v_mfma_f32_16x16x32_bf16 v[142:145], v[194:197], v[166:169], v[142:145]
	v_mfma_f32_16x16x32_bf16 v[134:137], v[198:201], v[166:169], v[134:137]
	v_mfma_f32_16x16x32_bf16 v[138:141], v[202:205], v[166:169], v[138:141]
	v_mfma_f32_16x16x32_bf16 v[130:133], v[206:209], v[166:169], v[130:133]
	s_waitcnt vmcnt(6)
	ds_write_b128 v235, v[30:33]
	ds_write_b128 v235, v[26:29] offset:8192
.LBB0_1150:
	s_lshl_b32 s2, s48, 8
	s_ashr_i32 s3, s2, 31
	s_lshl_b64 s[12:13], s[2:3], 11
	s_lshl_b32 s2, s22, 6
	s_ashr_i32 s3, s2, 31
	s_add_u32 s20, s11, s12
	s_addc_u32 s21, s24, s13
	s_lshl_b64 s[8:9], s[2:3], 1
	s_add_u32 s20, s20, s8
	s_addc_u32 s21, s21, s9
	global_load_dwordx4 v[30:33], v233, s[20:21]
	global_load_dwordx4 v[26:29], v234, s[20:21]
	s_andn2_b64 vcc, exec, s[14:15]
	ds_read_b128 v[166:169], v245
	v_mfma_f32_16x16x32_bf16 v[126:129], v[194:197], v[170:173], v[126:129]
	v_mfma_f32_16x16x32_bf16 v[118:121], v[198:201], v[170:173], v[118:121]
	v_mfma_f32_16x16x32_bf16 v[122:125], v[202:205], v[170:173], v[122:125]
	v_mfma_f32_16x16x32_bf16 v[114:117], v[206:209], v[170:173], v[114:117]
	ds_read_b128 v[170:173], v247 offset:4096
	v_mfma_f32_16x16x32_bf16 v[110:113], v[194:197], v[174:177], v[110:113]
	v_mfma_f32_16x16x32_bf16 v[102:105], v[198:201], v[174:177], v[102:105]
	v_mfma_f32_16x16x32_bf16 v[106:109], v[202:205], v[174:177], v[106:109]
	v_mfma_f32_16x16x32_bf16 v[66:69], v[206:209], v[174:177], v[66:69]
	ds_read_b128 v[210:213], v243
	ds_read_b128 v[214:217], v241
	ds_read_b128 v[218:221], v243 offset:4096
	ds_read_b128 v[222:225], v241 offset:4096
	ds_read_b128 v[174:177], v245 offset:4096
	s_waitcnt lgkmcnt(10)
	v_mfma_f32_16x16x32_bf16 v[98:101], v[194:197], v[178:181], v[98:101]
	v_mfma_f32_16x16x32_bf16 v[90:93], v[198:201], v[178:181], v[90:93]
	v_mfma_f32_16x16x32_bf16 v[94:97], v[202:205], v[178:181], v[94:97]
	v_mfma_f32_16x16x32_bf16 v[86:89], v[206:209], v[178:181], v[86:89]
	s_waitcnt vmcnt(6)
	ds_write_b128 v235, v[22:25] offset:16384
	ds_write_b128 v235, v[18:21] offset:24576
.LBB0_1152:
	global_load_dwordx4 v[18:21], v232, s[20:21]
	global_load_dwordx4 v[22:25], v231, s[20:21]
	s_and_b64 vcc, exec, s[2:3]
	ds_read_b128 v[178:181], v247 offset:8192
	s_waitcnt lgkmcnt(4)
	v_mfma_f32_16x16x32_bf16 v[82:85], v[194:197], v[182:185], v[82:85]
	v_mfma_f32_16x16x32_bf16 v[74:77], v[198:201], v[182:185], v[74:77]
	v_mfma_f32_16x16x32_bf16 v[78:81], v[202:205], v[182:185], v[78:81]
	v_mfma_f32_16x16x32_bf16 v[70:73], v[206:209], v[182:185], v[70:73]
	ds_read_b128 v[182:185], v245 offset:8192
	v_mfma_f32_16x16x32_bf16 v[62:65], v[194:197], v[186:189], v[62:65]
	v_mfma_f32_16x16x32_bf16 v[54:57], v[198:201], v[186:189], v[54:57]
	v_mfma_f32_16x16x32_bf16 v[58:61], v[202:205], v[186:189], v[58:61]
	v_mfma_f32_16x16x32_bf16 v[50:53], v[206:209], v[186:189], v[50:53]
	s_waitcnt vmcnt(6)
	ds_write_b128 v235, v[14:17] offset:32768
	ds_write_b128 v235, v[10:13] offset:40960
.LBB0_1154:
	s_lshl_b32 s14, s47, 8
	s_ashr_i32 s15, s14, 31
	s_lshl_b64 s[14:15], s[14:15], 11
	s_add_u32 s20, s25, s14
	s_addc_u32 s21, s26, s15
	s_add_u32 s8, s20, s8
	s_addc_u32 s9, s21, s9
	global_load_dwordx4 v[10:13], v234, s[8:9]
	global_load_dwordx4 v[14:17], v233, s[8:9]
	s_and_b64 vcc, exec, s[2:3]
	ds_read_b128 v[186:189], v247 offset:12288
	v_mfma_f32_16x16x32_bf16 v[46:49], v[194:197], v[190:193], v[46:49]
	v_mfma_f32_16x16x32_bf16 v[38:41], v[198:201], v[190:193], v[38:41]
	v_mfma_f32_16x16x32_bf16 v[42:45], v[202:205], v[190:193], v[42:45]
	v_mfma_f32_16x16x32_bf16 v[34:37], v[206:209], v[190:193], v[34:37]
	ds_read_b128 v[190:193], v245 offset:12288
	s_waitcnt lgkmcnt(8)
	v_mfma_f32_16x16x32_bf16 v[158:161], v[210:213], v[162:165], v[158:161]
	v_mfma_f32_16x16x32_bf16 v[150:153], v[214:217], v[162:165], v[150:153]
	v_mfma_f32_16x16x32_bf16 v[154:157], v[218:221], v[162:165], v[154:157]
	v_mfma_f32_16x16x32_bf16 v[146:149], v[222:225], v[162:165], v[146:149]
	v_mfma_f32_16x16x32_bf16 v[142:145], v[210:213], v[166:169], v[142:145]
	v_mfma_f32_16x16x32_bf16 v[134:137], v[214:217], v[166:169], v[134:137]
	v_mfma_f32_16x16x32_bf16 v[138:141], v[218:221], v[166:169], v[138:141]
	v_mfma_f32_16x16x32_bf16 v[130:133], v[222:225], v[166:169], v[130:133]
	s_waitcnt vmcnt(6)
	ds_write_b128 v235, v[6:9] offset:49152
	ds_write_b128 v235, v[2:5] offset:57344
.LBB0_1156:
	global_load_dwordx4 v[2:5], v232, s[8:9]
	global_load_dwordx4 v[6:9], v231, s[8:9]
	v_mfma_f32_16x16x32_bf16 v[126:129], v[210:213], v[170:173], v[126:129]
	v_mfma_f32_16x16x32_bf16 v[118:121], v[214:217], v[170:173], v[118:121]
	v_mfma_f32_16x16x32_bf16 v[122:125], v[218:221], v[170:173], v[122:125]
	v_mfma_f32_16x16x32_bf16 v[114:117], v[222:225], v[170:173], v[114:117]
	v_mfma_f32_16x16x32_bf16 v[110:113], v[210:213], v[174:177], v[110:113]
	v_mfma_f32_16x16x32_bf16 v[102:105], v[214:217], v[174:177], v[102:105]
	v_mfma_f32_16x16x32_bf16 v[106:109], v[218:221], v[174:177], v[106:109]
	v_mfma_f32_16x16x32_bf16 v[66:69], v[222:225], v[174:177], v[66:69]
	s_add_i32 s50, s22, 1
	s_cmp_lg_u32 s50, 16
	s_cbranch_scc1 .LBB0_1164
	s_add_i32 s31, s31, s28
	s_cmp_ge_i32 s31, s33
	s_cbranch_scc1 .LBB0_1163
	s_mov_b32 s8, s10
	s_cmpk_gt_i32 s31, 0x9f
	s_mov_b64 s[2:3], -1
	s_cbranch_scc0 .LBB0_1160
	s_lshl_b32 s2, s31, 2
	s_add_i32 s2, s2, 0x7ffffd80
	s_and_b32 s9, s2, 0x7ffffff8
	s_and_b32 s2, s31, 1
	s_or_b32 s47, s2, 20
	s_mov_b64 s[2:3], 0

.LBB0_1164:
	s_waitcnt lgkmcnt(0)
	s_barrier
	ds_read_b128 v[194:197], v250
	ds_read_b128 v[198:201], v248
	ds_read_b128 v[202:205], v250 offset:4096
	ds_read_b128 v[206:209], v248 offset:4096
	ds_read_b128 v[162:165], v254
	ds_read_b128 v[166:169], v252
	ds_read_b128 v[170:173], v254 offset:4096
	ds_read_b128 v[174:177], v252 offset:4096
	v_mfma_f32_16x16x32_bf16 v[98:101], v[210:213], v[178:181], v[98:101]
	v_mfma_f32_16x16x32_bf16 v[90:93], v[214:217], v[178:181], v[90:93]
	v_mfma_f32_16x16x32_bf16 v[94:97], v[218:221], v[178:181], v[94:97]
	v_mfma_f32_16x16x32_bf16 v[86:89], v[222:225], v[178:181], v[86:89]
	v_mfma_f32_16x16x32_bf16 v[82:85], v[210:213], v[182:185], v[82:85]
	v_mfma_f32_16x16x32_bf16 v[74:77], v[214:217], v[182:185], v[74:77]
	v_mfma_f32_16x16x32_bf16 v[78:81], v[218:221], v[182:185], v[78:81]
	v_mfma_f32_16x16x32_bf16 v[70:73], v[222:225], v[182:185], v[70:73]
	v_mfma_f32_16x16x32_bf16 v[62:65], v[210:213], v[186:189], v[62:65]
	v_mfma_f32_16x16x32_bf16 v[54:57], v[214:217], v[186:189], v[54:57]
	v_mfma_f32_16x16x32_bf16 v[58:61], v[218:221], v[186:189], v[58:61]
	v_mfma_f32_16x16x32_bf16 v[50:53], v[222:225], v[186:189], v[50:53]
	v_mfma_f32_16x16x32_bf16 v[46:49], v[210:213], v[190:193], v[46:49]
	v_mfma_f32_16x16x32_bf16 v[38:41], v[214:217], v[190:193], v[38:41]
	v_mfma_f32_16x16x32_bf16 v[42:45], v[218:221], v[190:193], v[42:45]
	v_mfma_f32_16x16x32_bf16 v[34:37], v[222:225], v[190:193], v[34:37]
	ds_read_b128 v[186:189], v254 offset:12288
	ds_read_b128 v[182:185], v252 offset:8192
	ds_read_b128 v[178:181], v254 offset:8192
	ds_read_b128 v[190:193], v252 offset:12288
	s_cmp_lt_i32 s41, s40
	s_cselect_b64 s[20:21], -1, 0
	s_cmp_ge_i32 s41, s40
	s_cselect_b64 s[8:9], -1, 0
	s_and_b64 vcc, exec, s[8:9]
	s_waitcnt lgkmcnt(4)
	v_mfma_f32_16x16x32_bf16 v[158:161], v[194:197], v[162:165], v[158:161]
	v_mfma_f32_16x16x32_bf16 v[150:153], v[198:201], v[162:165], v[150:153]
	v_mfma_f32_16x16x32_bf16 v[154:157], v[202:205], v[162:165], v[154:157]
	v_mfma_f32_16x16x32_bf16 v[146:149], v[206:209], v[162:165], v[146:149]
	ds_read_b128 v[162:165], v246
	s_waitcnt lgkmcnt(2)
	v_mfma_f32_16x16x32_bf16 v[142:145], v[194:197], v[166:169], v[142:145]
	v_mfma_f32_16x16x32_bf16 v[134:137], v[198:201], v[166:169], v[134:137]
	v_mfma_f32_16x16x32_bf16 v[138:141], v[202:205], v[166:169], v[138:141]
	v_mfma_f32_16x16x32_bf16 v[130:133], v[206:209], v[166:169], v[130:133]
	s_waitcnt vmcnt(6)
	ds_write_b128 v236, v[26:29]
	ds_write_b128 v236, v[30:33] offset:8192
.LBB0_1166:
	s_lshl_b32 s2, s50, 6
	s_ashr_i32 s3, s2, 31
	s_add_u32 s22, s11, s12
	s_addc_u32 s23, s24, s13
	s_lshl_b64 s[12:13], s[2:3], 1
	s_add_u32 s22, s22, s12
	s_addc_u32 s23, s23, s13
	global_load_dwordx4 v[30:33], v234, s[22:23]
	global_load_dwordx4 v[26:29], v233, s[22:23]
	s_andn2_b64 vcc, exec, s[20:21]
	ds_read_b128 v[166:169], v244
	v_mfma_f32_16x16x32_bf16 v[126:129], v[194:197], v[170:173], v[126:129]
	v_mfma_f32_16x16x32_bf16 v[118:121], v[198:201], v[170:173], v[118:121]
	v_mfma_f32_16x16x32_bf16 v[122:125], v[202:205], v[170:173], v[122:125]
	v_mfma_f32_16x16x32_bf16 v[114:117], v[206:209], v[170:173], v[114:117]
	ds_read_b128 v[170:173], v246 offset:4096
	v_mfma_f32_16x16x32_bf16 v[110:113], v[194:197], v[174:177], v[110:113]
	v_mfma_f32_16x16x32_bf16 v[102:105], v[198:201], v[174:177], v[102:105]
	v_mfma_f32_16x16x32_bf16 v[106:109], v[202:205], v[174:177], v[106:109]
	v_mfma_f32_16x16x32_bf16 v[66:69], v[206:209], v[174:177], v[66:69]
	ds_read_b128 v[210:213], v242
	ds_read_b128 v[214:217], v237
	ds_read_b128 v[218:221], v242 offset:4096
	ds_read_b128 v[222:225], v237 offset:4096
	ds_read_b128 v[174:177], v244 offset:4096
	s_waitcnt lgkmcnt(10)
	v_mfma_f32_16x16x32_bf16 v[98:101], v[194:197], v[178:181], v[98:101]
	v_mfma_f32_16x16x32_bf16 v[90:93], v[198:201], v[178:181], v[90:93]
	v_mfma_f32_16x16x32_bf16 v[94:97], v[202:205], v[178:181], v[94:97]
	v_mfma_f32_16x16x32_bf16 v[86:89], v[206:209], v[178:181], v[86:89]
	s_waitcnt vmcnt(6)
	ds_write_b128 v236, v[18:21] offset:16384
	ds_write_b128 v236, v[22:25] offset:24576
.LBB0_1168:
	global_load_dwordx4 v[22:25], v232, s[22:23]
	global_load_dwordx4 v[18:21], v231, s[22:23]
	s_and_b64 vcc, exec, s[2:3]
	ds_read_b128 v[178:181], v246 offset:8192
	s_waitcnt lgkmcnt(4)
	v_mfma_f32_16x16x32_bf16 v[82:85], v[194:197], v[182:185], v[82:85]
	v_mfma_f32_16x16x32_bf16 v[74:77], v[198:201], v[182:185], v[74:77]
	v_mfma_f32_16x16x32_bf16 v[78:81], v[202:205], v[182:185], v[78:81]
	v_mfma_f32_16x16x32_bf16 v[70:73], v[206:209], v[182:185], v[70:73]
	ds_read_b128 v[182:185], v244 offset:8192
	v_mfma_f32_16x16x32_bf16 v[62:65], v[194:197], v[186:189], v[62:65]
	v_mfma_f32_16x16x32_bf16 v[54:57], v[198:201], v[186:189], v[54:57]
	v_mfma_f32_16x16x32_bf16 v[58:61], v[202:205], v[186:189], v[58:61]
	v_mfma_f32_16x16x32_bf16 v[50:53], v[206:209], v[186:189], v[50:53]
	s_waitcnt vmcnt(6)
	ds_write_b128 v236, v[10:13] offset:32768
	ds_write_b128 v236, v[14:17] offset:40960
.LBB0_1170:
	s_add_u32 s14, s25, s14
	s_addc_u32 s15, s26, s15
	s_add_u32 s12, s14, s12
	s_addc_u32 s13, s15, s13
	global_load_dwordx4 v[14:17], v234, s[12:13]
	global_load_dwordx4 v[10:13], v233, s[12:13]
	s_and_b64 vcc, exec, s[2:3]
	ds_read_b128 v[186:189], v246 offset:12288
	v_mfma_f32_16x16x32_bf16 v[46:49], v[194:197], v[190:193], v[46:49]
	v_mfma_f32_16x16x32_bf16 v[38:41], v[198:201], v[190:193], v[38:41]
	v_mfma_f32_16x16x32_bf16 v[42:45], v[202:205], v[190:193], v[42:45]
	v_mfma_f32_16x16x32_bf16 v[34:37], v[206:209], v[190:193], v[34:37]
	ds_read_b128 v[190:193], v244 offset:12288
	s_waitcnt lgkmcnt(8)
	v_mfma_f32_16x16x32_bf16 v[158:161], v[210:213], v[162:165], v[158:161]
	v_mfma_f32_16x16x32_bf16 v[150:153], v[214:217], v[162:165], v[150:153]
	v_mfma_f32_16x16x32_bf16 v[154:157], v[218:221], v[162:165], v[154:157]
	v_mfma_f32_16x16x32_bf16 v[146:149], v[222:225], v[162:165], v[146:149]
	v_mfma_f32_16x16x32_bf16 v[142:145], v[210:213], v[166:169], v[142:145]
	v_mfma_f32_16x16x32_bf16 v[134:137], v[214:217], v[166:169], v[134:137]
	v_mfma_f32_16x16x32_bf16 v[138:141], v[218:221], v[166:169], v[138:141]
	v_mfma_f32_16x16x32_bf16 v[130:133], v[222:225], v[166:169], v[130:133]
	s_waitcnt vmcnt(6)
	ds_write_b128 v236, v[2:5] offset:49152
	ds_write_b128 v236, v[6:9] offset:57344
.LBB0_1172:
	global_load_dwordx4 v[6:9], v232, s[12:13]
	global_load_dwordx4 v[2:5], v231, s[12:13]
	v_mfma_f32_16x16x32_bf16 v[126:129], v[210:213], v[170:173], v[126:129]
	v_mfma_f32_16x16x32_bf16 v[118:121], v[214:217], v[170:173], v[118:121]
	v_mfma_f32_16x16x32_bf16 v[122:125], v[218:221], v[170:173], v[122:125]
	v_mfma_f32_16x16x32_bf16 v[114:117], v[222:225], v[170:173], v[114:117]
	v_mfma_f32_16x16x32_bf16 v[110:113], v[210:213], v[174:177], v[110:113]
	v_mfma_f32_16x16x32_bf16 v[102:105], v[214:217], v[174:177], v[102:105]
	v_mfma_f32_16x16x32_bf16 v[106:109], v[218:221], v[174:177], v[106:109]
	v_mfma_f32_16x16x32_bf16 v[66:69], v[222:225], v[174:177], v[66:69]
	s_add_i32 s22, s50, 1
	s_cmp_lg_u32 s22, 16
	s_cbranch_scc1 .LBB0_1180
	s_add_i32 s31, s31, s28
	s_cmp_ge_i32 s31, s33
	s_cbranch_scc1 .LBB0_1179
	s_mov_b32 s12, s10
	s_cmpk_gt_i32 s31, 0x9f
	s_mov_b64 s[2:3], -1
	s_cbranch_scc0 .LBB0_1176
	s_lshl_b32 s2, s31, 2
	s_add_i32 s2, s2, 0x7ffffd80
	s_and_b32 s13, s2, 0x7ffffff8
	s_and_b32 s2, s31, 1
	s_or_b32 s47, s2, 20
	s_mov_b64 s[2:3], 0

.Lnodef_I0_3:
	ds_read_b128 v[114:117], v247 offset:4096
	ds_read_b128 v[118:121], v245 offset:4096
	s_add_i32 s2, s36, -1
	s_cmp_lt_i32 s2, s35
	s_cselect_b64 s[8:9], -1, 0
	s_cmp_ge_i32 s2, s35
	s_waitcnt lgkmcnt(4)
	v_mfma_f32_16x16x32_bf16 v[58:61], v[122:125], v[90:93], v[58:61]
	v_mfma_f32_16x16x32_bf16 v[82:85], v[126:129], v[90:93], v[82:85]
	v_mfma_f32_16x16x32_bf16 v[86:89], v[130:133], v[90:93], v[86:89]
	v_mfma_f32_16x16x32_bf16 v[78:81], v[134:137], v[90:93], v[78:81]
	s_waitcnt lgkmcnt(3)
	v_mfma_f32_16x16x32_bf16 v[74:77], v[122:125], v[94:97], v[74:77]
	v_mfma_f32_16x16x32_bf16 v[66:69], v[126:129], v[94:97], v[66:69]
	v_mfma_f32_16x16x32_bf16 v[70:73], v[130:133], v[94:97], v[70:73]
	v_mfma_f32_16x16x32_bf16 v[62:65], v[134:137], v[94:97], v[62:65]
	s_waitcnt vmcnt(4)
	ds_write_b128 v238, v[22:25]
	ds_write_b128 v238, v[18:21] offset:8192
.LBB0_1205:
	s_lshl_b32 s2, s43, 8
	s_or_b32 s2, s2, s27
	s_ashr_i32 s3, s2, 31
	s_lshl_b64 s[12:13], s[2:3], 11
	s_lshl_b32 s2, s45, 6
	s_ashr_i32 s3, s2, 31
	s_add_u32 s14, s11, s12
	s_addc_u32 s15, s24, s13
	s_lshl_b64 s[20:21], s[2:3], 1
	s_add_u32 s2, s14, s20
	s_addc_u32 s3, s15, s21
	global_load_dwordx4 v[18:21], v237, s[2:3]
	global_load_dwordx4 v[22:25], v236, s[2:3]
	s_andn2_b64 vcc, exec, s[8:9]
	ds_read_b128 v[138:141], v243
	ds_read_b128 v[142:145], v241
	ds_read_b128 v[146:149], v243 offset:4096
	ds_read_b128 v[150:153], v241 offset:4096
	s_waitcnt lgkmcnt(0)
	v_mfma_f32_16x16x32_bf16 v[54:57], v[122:125], v[98:101], v[54:57]
	v_mfma_f32_16x16x32_bf16 v[46:49], v[126:129], v[98:101], v[46:49]
	v_mfma_f32_16x16x32_bf16 v[50:53], v[130:133], v[98:101], v[50:53]
	v_mfma_f32_16x16x32_bf16 v[42:45], v[134:137], v[98:101], v[42:45]
	s_waitcnt vmcnt(4)
	ds_write_b128 v238, v[14:17] offset:32768
	ds_write_b128 v238, v[10:13] offset:40960
.LBB0_1207:
	s_lshl_b32 s8, s42, 8
	s_ashr_i32 s9, s8, 31
	s_lshl_b64 s[14:15], s[8:9], 11
	s_add_u32 s8, s25, s14
	s_addc_u32 s9, s26, s15
	s_add_u32 s8, s8, s20
	s_addc_u32 s9, s9, s21
	global_load_dwordx4 v[10:13], v237, s[8:9]
	global_load_dwordx4 v[14:17], v236, s[8:9]
	s_and_b64 vcc, exec, s[2:3]
	v_mfma_f32_16x16x32_bf16 v[34:37], v[122:125], v[102:105], v[34:37]
	v_mfma_f32_16x16x32_bf16 v[30:33], v[126:129], v[102:105], v[30:33]
	v_mfma_f32_16x16x32_bf16 v[38:41], v[130:133], v[102:105], v[38:41]
	v_mfma_f32_16x16x32_bf16 v[26:29], v[134:137], v[102:105], v[26:29]
	s_waitcnt vmcnt(4)
	ds_write_b128 v238, v[6:9] offset:49152
	ds_write_b128 v238, v[2:5] offset:57344
.LBB0_1209:
	global_load_dwordx4 v[2:5], v235, s[8:9]
	global_load_dwordx4 v[6:9], v234, s[8:9]
	v_mfma_f32_16x16x32_bf16 v[58:61], v[138:141], v[106:109], v[58:61]
	v_mfma_f32_16x16x32_bf16 v[82:85], v[142:145], v[106:109], v[82:85]
	v_mfma_f32_16x16x32_bf16 v[86:89], v[146:149], v[106:109], v[86:89]
	v_mfma_f32_16x16x32_bf16 v[78:81], v[150:153], v[106:109], v[78:81]
	v_mfma_f32_16x16x32_bf16 v[74:77], v[138:141], v[110:113], v[74:77]
	v_mfma_f32_16x16x32_bf16 v[66:69], v[142:145], v[110:113], v[66:69]
	v_mfma_f32_16x16x32_bf16 v[70:73], v[146:149], v[110:113], v[70:73]
	v_mfma_f32_16x16x32_bf16 v[62:65], v[150:153], v[110:113], v[62:65]
	s_add_i32 s45, s45, 1
	s_cmp_lg_u32 s45, 16
	s_cbranch_scc1 .LBB0_1218
	s_add_i32 s22, s22, s23
	s_cmp_ge_i32 s22, s29
	s_cbranch_scc1 .LBB0_1217
	s_mov_b32 s8, s10
	s_cmpk_gt_i32 s22, 0xaf
	s_cbranch_scc1 .LBB0_1217
	s_cmpk_gt_i32 s22, 0x9f
	s_mov_b64 s[2:3], -1
	s_cbranch_scc0 .LBB0_1214
	s_lshl_b32 s2, s22, 2
	s_add_i32 s2, s2, 0x7ffffd80
	s_and_b32 s9, s2, 0x7ffffff8
	s_and_b32 s2, s22, 1
	s_or_b32 s42, s2, 20
	s_mov_b64 s[2:3], 0

.LBB0_1218:
	s_waitcnt lgkmcnt(0)
	s_barrier
	ds_read_b128 v[122:125], v250
	ds_read_b128 v[126:129], v248
	ds_read_b128 v[130:133], v250 offset:4096
	ds_read_b128 v[134:137], v248 offset:4096
	ds_read_b128 v[90:93], v254
	ds_read_b128 v[94:97], v252
	ds_read_b128 v[98:101], v254 offset:4096
	ds_read_b128 v[102:105], v252 offset:4096
	ds_read_b128 v[106:109], v246
	ds_read_b128 v[110:113], v244
	v_mfma_f32_16x16x32_bf16 v[54:57], v[138:141], v[114:117], v[54:57]
	v_mfma_f32_16x16x32_bf16 v[46:49], v[142:145], v[114:117], v[46:49]
	v_mfma_f32_16x16x32_bf16 v[50:53], v[146:149], v[114:117], v[50:53]
	v_mfma_f32_16x16x32_bf16 v[42:45], v[150:153], v[114:117], v[42:45]
	v_mfma_f32_16x16x32_bf16 v[34:37], v[138:141], v[118:121], v[34:37]
	v_mfma_f32_16x16x32_bf16 v[30:33], v[142:145], v[118:121], v[30:33]
	v_mfma_f32_16x16x32_bf16 v[38:41], v[146:149], v[118:121], v[38:41]
	v_mfma_f32_16x16x32_bf16 v[26:29], v[150:153], v[118:121], v[26:29]
	ds_read_b128 v[114:117], v246 offset:4096
	ds_read_b128 v[118:121], v244 offset:4096
	s_cmp_lt_i32 s36, s35
	s_cselect_b64 s[20:21], -1, 0
	s_cmp_ge_i32 s36, s35
	s_cselect_b64 s[8:9], -1, 0
	s_and_b64 vcc, exec, s[8:9]
	s_waitcnt lgkmcnt(4)
	v_mfma_f32_16x16x32_bf16 v[58:61], v[122:125], v[90:93], v[58:61]
	v_mfma_f32_16x16x32_bf16 v[82:85], v[126:129], v[90:93], v[82:85]
	v_mfma_f32_16x16x32_bf16 v[86:89], v[130:133], v[90:93], v[86:89]
	v_mfma_f32_16x16x32_bf16 v[78:81], v[134:137], v[90:93], v[78:81]
	s_waitcnt lgkmcnt(3)
	v_mfma_f32_16x16x32_bf16 v[74:77], v[122:125], v[94:97], v[74:77]
	v_mfma_f32_16x16x32_bf16 v[66:69], v[126:129], v[94:97], v[66:69]
	v_mfma_f32_16x16x32_bf16 v[70:73], v[130:133], v[94:97], v[70:73]
	v_mfma_f32_16x16x32_bf16 v[62:65], v[134:137], v[94:97], v[62:65]
	s_waitcnt vmcnt(4)
	ds_write_b128 v239, v[18:21]
	ds_write_b128 v239, v[22:25] offset:8192
.LBB0_1220:
	s_lshl_b32 s2, s45, 6
	s_ashr_i32 s3, s2, 31
	s_add_u32 s46, s11, s12
	s_addc_u32 s47, s24, s13
	s_lshl_b64 s[12:13], s[2:3], 1
	s_add_u32 s2, s46, s12
	s_addc_u32 s3, s47, s13
	global_load_dwordx4 v[22:25], v237, s[2:3]
	global_load_dwordx4 v[18:21], v236, s[2:3]
	s_andn2_b64 vcc, exec, s[20:21]
	ds_read_b128 v[138:141], v242
	ds_read_b128 v[142:145], v240
	ds_read_b128 v[146:149], v242 offset:4096
	ds_read_b128 v[150:153], v240 offset:4096
	s_waitcnt lgkmcnt(0)
	v_mfma_f32_16x16x32_bf16 v[54:57], v[122:125], v[98:101], v[54:57]
	v_mfma_f32_16x16x32_bf16 v[46:49], v[126:129], v[98:101], v[46:49]
	v_mfma_f32_16x16x32_bf16 v[50:53], v[130:133], v[98:101], v[50:53]
	v_mfma_f32_16x16x32_bf16 v[42:45], v[134:137], v[98:101], v[42:45]
	s_waitcnt vmcnt(4)
	ds_write_b128 v239, v[10:13] offset:32768
	ds_write_b128 v239, v[14:17] offset:40960
.LBB0_1222:
	s_add_u32 s14, s25, s14
	s_addc_u32 s15, s26, s15
	s_add_u32 s12, s14, s12
	s_addc_u32 s13, s15, s13
	global_load_dwordx4 v[14:17], v237, s[12:13]
	global_load_dwordx4 v[10:13], v236, s[12:13]
	s_and_b64 vcc, exec, s[2:3]
	v_mfma_f32_16x16x32_bf16 v[34:37], v[122:125], v[102:105], v[34:37]
	v_mfma_f32_16x16x32_bf16 v[30:33], v[126:129], v[102:105], v[30:33]
	v_mfma_f32_16x16x32_bf16 v[38:41], v[130:133], v[102:105], v[38:41]
	v_mfma_f32_16x16x32_bf16 v[26:29], v[134:137], v[102:105], v[26:29]
	s_waitcnt vmcnt(4)
	ds_write_b128 v239, v[2:5] offset:49152
	ds_write_b128 v239, v[6:9] offset:57344
.LBB0_1224:
	global_load_dwordx4 v[6:9], v235, s[12:13]
	global_load_dwordx4 v[2:5], v234, s[12:13]
	v_mfma_f32_16x16x32_bf16 v[58:61], v[138:141], v[106:109], v[58:61]
	v_mfma_f32_16x16x32_bf16 v[82:85], v[142:145], v[106:109], v[82:85]
	v_mfma_f32_16x16x32_bf16 v[86:89], v[146:149], v[106:109], v[86:89]
	v_mfma_f32_16x16x32_bf16 v[78:81], v[150:153], v[106:109], v[78:81]
	v_mfma_f32_16x16x32_bf16 v[74:77], v[138:141], v[110:113], v[74:77]
	v_mfma_f32_16x16x32_bf16 v[66:69], v[142:145], v[110:113], v[66:69]
	v_mfma_f32_16x16x32_bf16 v[70:73], v[146:149], v[110:113], v[70:73]
	v_mfma_f32_16x16x32_bf16 v[62:65], v[150:153], v[110:113], v[62:65]
	s_add_i32 s45, s45, 1
	s_cmp_lg_u32 s45, 16
	s_cbranch_scc1 .LBB0_1233
	s_add_i32 s22, s22, s23
	s_cmp_ge_i32 s22, s29
	s_cbranch_scc1 .LBB0_1232
	s_mov_b32 s12, s10
	s_cmpk_gt_i32 s22, 0xaf
	s_cbranch_scc1 .LBB0_1232
	s_cmpk_gt_i32 s22, 0x9f
	s_mov_b64 s[2:3], -1
	s_cbranch_scc0 .LBB0_1229
	s_lshl_b32 s2, s22, 2
	s_add_i32 s2, s2, 0x7ffffd80
	s_and_b32 s13, s2, 0x7ffffff8
	s_and_b32 s2, s22, 1
	s_or_b32 s42, s2, 20
	s_mov_b64 s[2:3], 0

.Lnodef_J0_4:
	ds_read_b128 v[186:189], v255 offset:12288
	ds_read_b128 v[182:185], v253 offset:8192
	ds_read_b128 v[178:181], v255 offset:8192
	ds_read_b128 v[190:193], v253 offset:12288
	s_add_i32 s2, s39, -1
	s_cmp_lt_i32 s2, s41
	s_cselect_b64 s[22:23], -1, 0
	s_cmp_ge_i32 s2, s41
	s_waitcnt lgkmcnt(4)
	v_mfma_f32_16x16x32_bf16 v[158:161], v[194:197], v[162:165], v[158:161]
	v_mfma_f32_16x16x32_bf16 v[154:157], v[198:201], v[162:165], v[154:157]
	v_mfma_f32_16x16x32_bf16 v[150:153], v[202:205], v[162:165], v[150:153]
	v_mfma_f32_16x16x32_bf16 v[146:149], v[206:209], v[162:165], v[146:149]
	ds_read_b128 v[162:165], v247
	s_waitcnt lgkmcnt(2)
	v_mfma_f32_16x16x32_bf16 v[142:145], v[194:197], v[166:169], v[142:145]
	v_mfma_f32_16x16x32_bf16 v[138:141], v[198:201], v[166:169], v[138:141]
	v_mfma_f32_16x16x32_bf16 v[134:137], v[202:205], v[166:169], v[134:137]
	v_mfma_f32_16x16x32_bf16 v[130:133], v[206:209], v[166:169], v[130:133]
	s_waitcnt vmcnt(6)
	ds_write_b128 v235, v[30:33]
	ds_write_b128 v235, v[26:29] offset:8192
.LBB0_1304:
	s_lshl_b32 s2, s49, 8
	s_mul_i32 s20, s49, 0xb0000
	s_mul_hi_i32 s21, s2, 0xb00
	s_lshl_b32 s2, s26, 6
	s_ashr_i32 s3, s2, 31
	s_lshl_b64 s[6:7], s[20:21], 1
	s_add_u32 s24, s29, s6
	s_addc_u32 s25, s30, s7
	s_lshl_b64 s[6:7], s[2:3], 1
	s_add_u32 s24, s24, s6
	s_addc_u32 s25, s25, s7
	global_load_dwordx4 v[26:29], v234, s[24:25]
	global_load_dwordx4 v[30:33], v233, s[24:25]
	s_andn2_b64 vcc, exec, s[22:23]
	ds_read_b128 v[166:169], v245
	v_mfma_f32_16x16x32_bf16 v[126:129], v[194:197], v[170:173], v[126:129]
	v_mfma_f32_16x16x32_bf16 v[122:125], v[198:201], v[170:173], v[122:125]
	v_mfma_f32_16x16x32_bf16 v[118:121], v[202:205], v[170:173], v[118:121]
	v_mfma_f32_16x16x32_bf16 v[114:117], v[206:209], v[170:173], v[114:117]
	ds_read_b128 v[170:173], v247 offset:4096
	v_mfma_f32_16x16x32_bf16 v[110:113], v[194:197], v[174:177], v[110:113]
	v_mfma_f32_16x16x32_bf16 v[106:109], v[198:201], v[174:177], v[106:109]
	v_mfma_f32_16x16x32_bf16 v[102:105], v[202:205], v[174:177], v[102:105]
	v_mfma_f32_16x16x32_bf16 v[82:85], v[206:209], v[174:177], v[82:85]
	ds_read_b128 v[210:213], v243
	ds_read_b128 v[214:217], v241
	ds_read_b128 v[218:221], v243 offset:4096
	ds_read_b128 v[222:225], v241 offset:4096
	ds_read_b128 v[174:177], v245 offset:4096
	s_waitcnt lgkmcnt(10)
	v_mfma_f32_16x16x32_bf16 v[98:101], v[194:197], v[178:181], v[98:101]
	v_mfma_f32_16x16x32_bf16 v[94:97], v[198:201], v[178:181], v[94:97]
	v_mfma_f32_16x16x32_bf16 v[90:93], v[202:205], v[178:181], v[90:93]
	v_mfma_f32_16x16x32_bf16 v[86:89], v[206:209], v[178:181], v[86:89]
	s_waitcnt vmcnt(6)
	ds_write_b128 v235, v[22:25] offset:16384
	ds_write_b128 v235, v[18:21] offset:24576
.LBB0_1306:
	global_load_dwordx4 v[18:21], v232, s[24:25]
	global_load_dwordx4 v[22:25], v231, s[24:25]
	s_and_b64 vcc, exec, s[2:3]
	ds_read_b128 v[178:181], v247 offset:8192
	s_waitcnt lgkmcnt(4)
	v_mfma_f32_16x16x32_bf16 v[78:81], v[194:197], v[182:185], v[78:81]
	v_mfma_f32_16x16x32_bf16 v[74:77], v[198:201], v[182:185], v[74:77]
	v_mfma_f32_16x16x32_bf16 v[70:73], v[202:205], v[182:185], v[70:73]
	v_mfma_f32_16x16x32_bf16 v[66:69], v[206:209], v[182:185], v[66:69]
	ds_read_b128 v[182:185], v245 offset:8192
	v_mfma_f32_16x16x32_bf16 v[62:65], v[194:197], v[186:189], v[62:65]
	v_mfma_f32_16x16x32_bf16 v[58:61], v[198:201], v[186:189], v[58:61]
	v_mfma_f32_16x16x32_bf16 v[54:57], v[202:205], v[186:189], v[54:57]
	v_mfma_f32_16x16x32_bf16 v[50:53], v[206:209], v[186:189], v[50:53]
	s_waitcnt vmcnt(6)
	ds_write_b128 v235, v[14:17] offset:32768
	ds_write_b128 v235, v[10:13] offset:40960
.LBB0_1308:
	s_lshl_b32 s23, s48, 8
	s_mul_i32 s22, s48, 0xb0000
	s_mul_hi_i32 s23, s23, 0xb00
	s_lshl_b64 s[24:25], s[22:23], 1
	s_add_u32 s24, s31, s24
	s_addc_u32 s25, s33, s25
	s_add_u32 s6, s24, s6
	s_addc_u32 s7, s25, s7
	global_load_dwordx4 v[10:13], v234, s[6:7]
	global_load_dwordx4 v[14:17], v233, s[6:7]
	s_and_b64 vcc, exec, s[2:3]
	ds_read_b128 v[186:189], v247 offset:12288
	v_mfma_f32_16x16x32_bf16 v[46:49], v[194:197], v[190:193], v[46:49]
	v_mfma_f32_16x16x32_bf16 v[42:45], v[198:201], v[190:193], v[42:45]
	v_mfma_f32_16x16x32_bf16 v[38:41], v[202:205], v[190:193], v[38:41]
	v_mfma_f32_16x16x32_bf16 v[34:37], v[206:209], v[190:193], v[34:37]
	ds_read_b128 v[190:193], v245 offset:12288
	s_waitcnt lgkmcnt(8)
	v_mfma_f32_16x16x32_bf16 v[158:161], v[210:213], v[162:165], v[158:161]
	v_mfma_f32_16x16x32_bf16 v[154:157], v[214:217], v[162:165], v[154:157]
	v_mfma_f32_16x16x32_bf16 v[150:153], v[218:221], v[162:165], v[150:153]
	v_mfma_f32_16x16x32_bf16 v[146:149], v[222:225], v[162:165], v[146:149]
	v_mfma_f32_16x16x32_bf16 v[142:145], v[210:213], v[166:169], v[142:145]
	v_mfma_f32_16x16x32_bf16 v[138:141], v[214:217], v[166:169], v[138:141]
	v_mfma_f32_16x16x32_bf16 v[134:137], v[218:221], v[166:169], v[134:137]
	v_mfma_f32_16x16x32_bf16 v[130:133], v[222:225], v[166:169], v[130:133]
	s_waitcnt vmcnt(6)
	ds_write_b128 v235, v[6:9] offset:49152
	ds_write_b128 v235, v[2:5] offset:57344
.LBB0_1310:
	global_load_dwordx4 v[2:5], v232, s[6:7]
	global_load_dwordx4 v[6:9], v231, s[6:7]
	v_mfma_f32_16x16x32_bf16 v[126:129], v[210:213], v[170:173], v[126:129]
	v_mfma_f32_16x16x32_bf16 v[122:125], v[214:217], v[170:173], v[122:125]
	v_mfma_f32_16x16x32_bf16 v[118:121], v[218:221], v[170:173], v[118:121]
	v_mfma_f32_16x16x32_bf16 v[114:117], v[222:225], v[170:173], v[114:117]
	v_mfma_f32_16x16x32_bf16 v[110:113], v[210:213], v[174:177], v[110:113]
	v_mfma_f32_16x16x32_bf16 v[106:109], v[214:217], v[174:177], v[106:109]
	v_mfma_f32_16x16x32_bf16 v[102:105], v[218:221], v[174:177], v[102:105]
	v_mfma_f32_16x16x32_bf16 v[82:85], v[222:225], v[174:177], v[82:85]
	s_add_i32 s51, s26, 1
	s_cmp_lg_u32 s51, 44
	s_cbranch_scc1 .LBB0_1314
	s_add_i32 s28, s28, s11
	s_cmp_gt_i32 s28, 31
	s_cbranch_scc1 .LBB0_1313
	s_ashr_i32 s3, s28, 31
	s_lshr_b32 s3, s3, 27
	s_add_i32 s3, s28, s3
	s_ashr_i32 s3, s3, 5
	s_mov_b32 s2, s10
	s_lshl_b32 s6, s3, 6
	s_lshl_b32 s7, s28, 1
	s_sub_i32 s6, s7, s6
	s_and_b32 s2, s2, 7
	s_and_b32 s6, s6, -8
	s_lshl_b32 s3, s3, 2
	s_and_b32 s7, s28, 3
	s_or_b32 s49, s2, s6
	s_or_b32 s48, s3, s7
	s_lshl_b32 s2, s49, 8
	s_mul_hi_i32 s21, s2, 0xb00
	s_lshl_b32 s2, s48, 8
	s_mul_i32 s20, s49, 0xb0000
	s_mul_i32 s22, s48, 0xb0000
	s_mul_hi_i32 s23, s2, 0xb00

.LBB0_1314:
	s_waitcnt lgkmcnt(0)
	s_barrier
	ds_read_b128 v[194:197], v250
	ds_read_b128 v[198:201], v248
	ds_read_b128 v[202:205], v250 offset:4096
	ds_read_b128 v[206:209], v248 offset:4096
	ds_read_b128 v[162:165], v254
	ds_read_b128 v[166:169], v252
	ds_read_b128 v[170:173], v254 offset:4096
	ds_read_b128 v[174:177], v252 offset:4096
	v_mfma_f32_16x16x32_bf16 v[98:101], v[210:213], v[178:181], v[98:101]
	v_mfma_f32_16x16x32_bf16 v[94:97], v[214:217], v[178:181], v[94:97]
	v_mfma_f32_16x16x32_bf16 v[90:93], v[218:221], v[178:181], v[90:93]
	v_mfma_f32_16x16x32_bf16 v[86:89], v[222:225], v[178:181], v[86:89]
	v_mfma_f32_16x16x32_bf16 v[78:81], v[210:213], v[182:185], v[78:81]
	v_mfma_f32_16x16x32_bf16 v[74:77], v[214:217], v[182:185], v[74:77]
	v_mfma_f32_16x16x32_bf16 v[70:73], v[218:221], v[182:185], v[70:73]
	v_mfma_f32_16x16x32_bf16 v[66:69], v[222:225], v[182:185], v[66:69]
	v_mfma_f32_16x16x32_bf16 v[62:65], v[210:213], v[186:189], v[62:65]
	v_mfma_f32_16x16x32_bf16 v[58:61], v[214:217], v[186:189], v[58:61]
	v_mfma_f32_16x16x32_bf16 v[54:57], v[218:221], v[186:189], v[54:57]
	v_mfma_f32_16x16x32_bf16 v[50:53], v[222:225], v[186:189], v[50:53]
	v_mfma_f32_16x16x32_bf16 v[46:49], v[210:213], v[190:193], v[46:49]
	v_mfma_f32_16x16x32_bf16 v[42:45], v[214:217], v[190:193], v[42:45]
	v_mfma_f32_16x16x32_bf16 v[38:41], v[218:221], v[190:193], v[38:41]
	v_mfma_f32_16x16x32_bf16 v[34:37], v[222:225], v[190:193], v[34:37]
	ds_read_b128 v[186:189], v254 offset:12288
	ds_read_b128 v[182:185], v252 offset:8192
	ds_read_b128 v[178:181], v254 offset:8192
	ds_read_b128 v[190:193], v252 offset:12288
	s_cmp_lt_i32 s39, s41
	s_cselect_b64 s[24:25], -1, 0
	s_cmp_ge_i32 s39, s41
	s_cselect_b64 s[6:7], -1, 0
	s_and_b64 vcc, exec, s[6:7]
	s_waitcnt lgkmcnt(4)
	v_mfma_f32_16x16x32_bf16 v[158:161], v[194:197], v[162:165], v[158:161]
	v_mfma_f32_16x16x32_bf16 v[154:157], v[198:201], v[162:165], v[154:157]
	v_mfma_f32_16x16x32_bf16 v[150:153], v[202:205], v[162:165], v[150:153]
	v_mfma_f32_16x16x32_bf16 v[146:149], v[206:209], v[162:165], v[146:149]
	ds_read_b128 v[162:165], v246
	s_waitcnt lgkmcnt(2)
	v_mfma_f32_16x16x32_bf16 v[142:145], v[194:197], v[166:169], v[142:145]
	v_mfma_f32_16x16x32_bf16 v[138:141], v[198:201], v[166:169], v[138:141]
	v_mfma_f32_16x16x32_bf16 v[134:137], v[202:205], v[166:169], v[134:137]
	v_mfma_f32_16x16x32_bf16 v[130:133], v[206:209], v[166:169], v[130:133]
	s_waitcnt vmcnt(6)
	ds_write_b128 v236, v[26:29]
	ds_write_b128 v236, v[30:33] offset:8192
.LBB0_1316:
	s_lshl_b32 s2, s51, 6
	s_ashr_i32 s3, s2, 31
	s_lshl_b64 s[20:21], s[20:21], 1
	s_add_u32 s26, s29, s20
	s_addc_u32 s27, s30, s21
	s_lshl_b64 s[20:21], s[2:3], 1
	s_add_u32 s26, s26, s20
	s_addc_u32 s27, s27, s21
	global_load_dwordx4 v[30:33], v234, s[26:27]
	global_load_dwordx4 v[26:29], v233, s[26:27]
	s_andn2_b64 vcc, exec, s[24:25]
	ds_read_b128 v[166:169], v244
	v_mfma_f32_16x16x32_bf16 v[126:129], v[194:197], v[170:173], v[126:129]
	v_mfma_f32_16x16x32_bf16 v[122:125], v[198:201], v[170:173], v[122:125]
	v_mfma_f32_16x16x32_bf16 v[118:121], v[202:205], v[170:173], v[118:121]
	v_mfma_f32_16x16x32_bf16 v[114:117], v[206:209], v[170:173], v[114:117]
	ds_read_b128 v[170:173], v246 offset:4096
	v_mfma_f32_16x16x32_bf16 v[110:113], v[194:197], v[174:177], v[110:113]
	v_mfma_f32_16x16x32_bf16 v[106:109], v[198:201], v[174:177], v[106:109]
	v_mfma_f32_16x16x32_bf16 v[102:105], v[202:205], v[174:177], v[102:105]
	v_mfma_f32_16x16x32_bf16 v[82:85], v[206:209], v[174:177], v[82:85]
	ds_read_b128 v[210:213], v242
	ds_read_b128 v[214:217], v237
	ds_read_b128 v[218:221], v242 offset:4096
	ds_read_b128 v[222:225], v237 offset:4096
	ds_read_b128 v[174:177], v244 offset:4096
	s_waitcnt lgkmcnt(10)
	v_mfma_f32_16x16x32_bf16 v[98:101], v[194:197], v[178:181], v[98:101]
	v_mfma_f32_16x16x32_bf16 v[94:97], v[198:201], v[178:181], v[94:97]
	v_mfma_f32_16x16x32_bf16 v[90:93], v[202:205], v[178:181], v[90:93]
	v_mfma_f32_16x16x32_bf16 v[86:89], v[206:209], v[178:181], v[86:89]
	s_waitcnt vmcnt(6)
	ds_write_b128 v236, v[18:21] offset:16384
	ds_write_b128 v236, v[22:25] offset:24576
.LBB0_1318:
	global_load_dwordx4 v[22:25], v232, s[26:27]
	global_load_dwordx4 v[18:21], v231, s[26:27]
	s_and_b64 vcc, exec, s[2:3]
	ds_read_b128 v[178:181], v246 offset:8192
	s_waitcnt lgkmcnt(4)
	v_mfma_f32_16x16x32_bf16 v[78:81], v[194:197], v[182:185], v[78:81]
	v_mfma_f32_16x16x32_bf16 v[74:77], v[198:201], v[182:185], v[74:77]
	v_mfma_f32_16x16x32_bf16 v[70:73], v[202:205], v[182:185], v[70:73]
	v_mfma_f32_16x16x32_bf16 v[66:69], v[206:209], v[182:185], v[66:69]
	ds_read_b128 v[182:185], v244 offset:8192
	v_mfma_f32_16x16x32_bf16 v[62:65], v[194:197], v[186:189], v[62:65]
	v_mfma_f32_16x16x32_bf16 v[58:61], v[198:201], v[186:189], v[58:61]
	v_mfma_f32_16x16x32_bf16 v[54:57], v[202:205], v[186:189], v[54:57]
	v_mfma_f32_16x16x32_bf16 v[50:53], v[206:209], v[186:189], v[50:53]
	s_waitcnt vmcnt(6)
	ds_write_b128 v236, v[10:13] offset:32768
	ds_write_b128 v236, v[14:17] offset:40960
.LBB0_1320:
	s_lshl_b64 s[22:23], s[22:23], 1
	s_add_u32 s22, s31, s22
	s_addc_u32 s23, s33, s23
	s_add_u32 s20, s22, s20
	s_addc_u32 s21, s23, s21
	global_load_dwordx4 v[14:17], v234, s[20:21]
	global_load_dwordx4 v[10:13], v233, s[20:21]
	s_and_b64 vcc, exec, s[2:3]
	ds_read_b128 v[186:189], v246 offset:12288
	v_mfma_f32_16x16x32_bf16 v[46:49], v[194:197], v[190:193], v[46:49]
	v_mfma_f32_16x16x32_bf16 v[42:45], v[198:201], v[190:193], v[42:45]
	v_mfma_f32_16x16x32_bf16 v[38:41], v[202:205], v[190:193], v[38:41]
	v_mfma_f32_16x16x32_bf16 v[34:37], v[206:209], v[190:193], v[34:37]
	ds_read_b128 v[190:193], v244 offset:12288
	s_waitcnt lgkmcnt(8)
	v_mfma_f32_16x16x32_bf16 v[158:161], v[210:213], v[162:165], v[158:161]
	v_mfma_f32_16x16x32_bf16 v[154:157], v[214:217], v[162:165], v[154:157]
	v_mfma_f32_16x16x32_bf16 v[150:153], v[218:221], v[162:165], v[150:153]
	v_mfma_f32_16x16x32_bf16 v[146:149], v[222:225], v[162:165], v[146:149]
	v_mfma_f32_16x16x32_bf16 v[142:145], v[210:213], v[166:169], v[142:145]
	v_mfma_f32_16x16x32_bf16 v[138:141], v[214:217], v[166:169], v[138:141]
	v_mfma_f32_16x16x32_bf16 v[134:137], v[218:221], v[166:169], v[134:137]
	v_mfma_f32_16x16x32_bf16 v[130:133], v[222:225], v[166:169], v[130:133]
	s_waitcnt vmcnt(6)
	ds_write_b128 v236, v[2:5] offset:49152
	ds_write_b128 v236, v[6:9] offset:57344
.LBB0_1322:
	global_load_dwordx4 v[6:9], v232, s[20:21]
	global_load_dwordx4 v[2:5], v231, s[20:21]
	v_mfma_f32_16x16x32_bf16 v[126:129], v[210:213], v[170:173], v[126:129]
	v_mfma_f32_16x16x32_bf16 v[122:125], v[214:217], v[170:173], v[122:125]
	v_mfma_f32_16x16x32_bf16 v[118:121], v[218:221], v[170:173], v[118:121]
	v_mfma_f32_16x16x32_bf16 v[114:117], v[222:225], v[170:173], v[114:117]
	v_mfma_f32_16x16x32_bf16 v[110:113], v[210:213], v[174:177], v[110:113]
	v_mfma_f32_16x16x32_bf16 v[106:109], v[214:217], v[174:177], v[106:109]
	v_mfma_f32_16x16x32_bf16 v[102:105], v[218:221], v[174:177], v[102:105]
	v_mfma_f32_16x16x32_bf16 v[82:85], v[222:225], v[174:177], v[82:85]
	s_add_i32 s26, s51, 1
	s_cmp_lg_u32 s26, 44
	s_cbranch_scc1 .LBB0_1326
	s_add_i32 s28, s28, s11
	s_cmp_gt_i32 s28, 31
	s_cbranch_scc1 .LBB0_1325
	s_ashr_i32 s3, s28, 31
	s_lshr_b32 s3, s3, 27
	s_add_i32 s3, s28, s3
	s_ashr_i32 s3, s3, 5
	s_mov_b32 s2, s10
	s_lshl_b32 s20, s3, 6
	s_lshl_b32 s21, s28, 1
	s_sub_i32 s20, s21, s20
	s_and_b32 s2, s2, 7
	s_and_b32 s20, s20, -8
	s_lshl_b32 s3, s3, 2
	s_and_b32 s21, s28, 3
	s_or_b32 s48, s3, s21
	s_or_b32 s49, s2, s20

.Lnodef_G1_6:
	ds_read_b128 v[186:189], v255 offset:12288
	ds_read_b128 v[182:185], v253 offset:8192
	ds_read_b128 v[178:181], v255 offset:8192
	ds_read_b128 v[190:193], v253 offset:12288
	s_add_i32 s2, s40, -1
	s_cmp_lt_i32 s2, s35
	s_cselect_b64 s[22:23], -1, 0
	s_cmp_ge_i32 s2, s35
	s_waitcnt lgkmcnt(4)
	v_mfma_f32_16x16x32_bf16 v[158:161], v[194:197], v[162:165], v[158:161]
	v_mfma_f32_16x16x32_bf16 v[154:157], v[198:201], v[162:165], v[154:157]
	v_mfma_f32_16x16x32_bf16 v[150:153], v[202:205], v[162:165], v[150:153]
	v_mfma_f32_16x16x32_bf16 v[146:149], v[206:209], v[162:165], v[146:149]
	ds_read_b128 v[162:165], v247
	s_waitcnt lgkmcnt(2)
	v_mfma_f32_16x16x32_bf16 v[142:145], v[194:197], v[166:169], v[142:145]
	v_mfma_f32_16x16x32_bf16 v[138:141], v[198:201], v[166:169], v[138:141]
	v_mfma_f32_16x16x32_bf16 v[134:137], v[202:205], v[166:169], v[134:137]
	v_mfma_f32_16x16x32_bf16 v[130:133], v[206:209], v[166:169], v[130:133]
	s_waitcnt vmcnt(6)
	ds_write_b128 v235, v[30:33]
	ds_write_b128 v235, v[26:29] offset:8192
.LBB0_2205:
	s_lshl_b32 s6, s49, 8
	s_ashr_i32 s7, s6, 31
	s_lshl_b32 s2, s26, 6
	s_ashr_i32 s3, s2, 31
	s_lshl_b64 s[20:21], s[6:7], 11
	s_add_u32 s24, s29, s20
	s_addc_u32 s25, s30, s21
	s_lshl_b64 s[20:21], s[2:3], 1
	s_add_u32 s24, s24, s20
	s_addc_u32 s25, s25, s21
	global_load_dwordx4 v[30:33], v233, s[24:25]
	global_load_dwordx4 v[26:29], v234, s[24:25]
	s_andn2_b64 vcc, exec, s[22:23]
	ds_read_b128 v[166:169], v245
	v_mfma_f32_16x16x32_bf16 v[126:129], v[194:197], v[170:173], v[126:129]
	v_mfma_f32_16x16x32_bf16 v[122:125], v[198:201], v[170:173], v[122:125]
	v_mfma_f32_16x16x32_bf16 v[118:121], v[202:205], v[170:173], v[118:121]
	v_mfma_f32_16x16x32_bf16 v[114:117], v[206:209], v[170:173], v[114:117]
	ds_read_b128 v[170:173], v247 offset:4096
	v_mfma_f32_16x16x32_bf16 v[110:113], v[194:197], v[174:177], v[110:113]
	v_mfma_f32_16x16x32_bf16 v[106:109], v[198:201], v[174:177], v[106:109]
	v_mfma_f32_16x16x32_bf16 v[102:105], v[202:205], v[174:177], v[102:105]
	v_mfma_f32_16x16x32_bf16 v[82:85], v[206:209], v[174:177], v[82:85]
	ds_read_b128 v[210:213], v243
	ds_read_b128 v[214:217], v241
	ds_read_b128 v[218:221], v243 offset:4096
	ds_read_b128 v[222:225], v241 offset:4096
	ds_read_b128 v[174:177], v245 offset:4096
	s_waitcnt lgkmcnt(10)
	v_mfma_f32_16x16x32_bf16 v[98:101], v[194:197], v[178:181], v[98:101]
	v_mfma_f32_16x16x32_bf16 v[94:97], v[198:201], v[178:181], v[94:97]
	v_mfma_f32_16x16x32_bf16 v[90:93], v[202:205], v[178:181], v[90:93]
	v_mfma_f32_16x16x32_bf16 v[86:89], v[206:209], v[178:181], v[86:89]
	s_waitcnt vmcnt(6)
	ds_write_b128 v235, v[22:25] offset:16384
	ds_write_b128 v235, v[18:21] offset:24576

.LBB0_2209:
	s_lshl_b32 s22, s48, 8
	s_ashr_i32 s23, s22, 31
	s_lshl_b64 s[24:25], s[22:23], 11
	s_add_u32 s24, s31, s24
	s_addc_u32 s25, s33, s25
	s_add_u32 s20, s24, s20
	s_addc_u32 s21, s25, s21
	global_load_dwordx4 v[10:13], v234, s[20:21]
	global_load_dwordx4 v[14:17], v233, s[20:21]
	s_and_b64 vcc, exec, s[2:3]
	ds_read_b128 v[186:189], v247 offset:12288
	v_mfma_f32_16x16x32_bf16 v[46:49], v[194:197], v[190:193], v[46:49]
	v_mfma_f32_16x16x32_bf16 v[42:45], v[198:201], v[190:193], v[42:45]
	v_mfma_f32_16x16x32_bf16 v[38:41], v[202:205], v[190:193], v[38:41]
	v_mfma_f32_16x16x32_bf16 v[34:37], v[206:209], v[190:193], v[34:37]
	ds_read_b128 v[190:193], v245 offset:12288
	s_waitcnt lgkmcnt(8)
	v_mfma_f32_16x16x32_bf16 v[158:161], v[210:213], v[162:165], v[158:161]
	v_mfma_f32_16x16x32_bf16 v[154:157], v[214:217], v[162:165], v[154:157]
	v_mfma_f32_16x16x32_bf16 v[150:153], v[218:221], v[162:165], v[150:153]
	v_mfma_f32_16x16x32_bf16 v[146:149], v[222:225], v[162:165], v[146:149]
	v_mfma_f32_16x16x32_bf16 v[142:145], v[210:213], v[166:169], v[142:145]
	v_mfma_f32_16x16x32_bf16 v[138:141], v[214:217], v[166:169], v[138:141]
	v_mfma_f32_16x16x32_bf16 v[134:137], v[218:221], v[166:169], v[134:137]
	v_mfma_f32_16x16x32_bf16 v[130:133], v[222:225], v[166:169], v[130:133]
	s_waitcnt vmcnt(6)
	ds_write_b128 v235, v[6:9] offset:49152
	ds_write_b128 v235, v[2:5] offset:57344
.LBB0_2211:
	global_load_dwordx4 v[2:5], v232, s[20:21]
	global_load_dwordx4 v[6:9], v231, s[20:21]
	v_mfma_f32_16x16x32_bf16 v[126:129], v[210:213], v[170:173], v[126:129]
	v_mfma_f32_16x16x32_bf16 v[122:125], v[214:217], v[170:173], v[122:125]
	v_mfma_f32_16x16x32_bf16 v[118:121], v[218:221], v[170:173], v[118:121]
	v_mfma_f32_16x16x32_bf16 v[114:117], v[222:225], v[170:173], v[114:117]
	v_mfma_f32_16x16x32_bf16 v[110:113], v[210:213], v[174:177], v[110:113]
	v_mfma_f32_16x16x32_bf16 v[106:109], v[214:217], v[174:177], v[106:109]
	v_mfma_f32_16x16x32_bf16 v[102:105], v[218:221], v[174:177], v[102:105]
	v_mfma_f32_16x16x32_bf16 v[82:85], v[222:225], v[174:177], v[82:85]
	s_lshl_b64 s[2:3], s[6:7], 10
	s_lshl_b64 s[20:21], s[22:23], 10
	s_add_i32 s51, s26, 1
	s_cmp_lg_u32 s51, 16
	s_cbranch_scc1 .LBB0_2215
	s_add_i32 s28, s28, s11
	s_cmp_gt_i32 s28, 31
	s_cbranch_scc1 .LBB0_2214
	s_ashr_i32 s3, s28, 31
	s_lshr_b32 s3, s3, 27
	s_add_i32 s3, s28, s3
	s_ashr_i32 s3, s3, 5
	s_mov_b32 s2, s10
	s_lshl_b32 s6, s3, 6
	s_lshl_b32 s7, s28, 1
	s_sub_i32 s6, s7, s6
	s_and_b32 s2, s2, 7
	s_and_b32 s6, s6, -8
	s_lshl_b32 s3, s3, 2
	s_and_b32 s7, s28, 3
	s_or_b32 s48, s3, s7
	s_or_b32 s49, s2, s6
	s_lshl_b32 s2, s49, 8
	s_lshl_b32 s6, s48, 8
	s_ashr_i32 s3, s2, 31
	s_ashr_i32 s7, s6, 31
	s_lshl_b64 s[2:3], s[2:3], 10
	s_lshl_b64 s[20:21], s[6:7], 10

.LBB0_2215:
	s_waitcnt lgkmcnt(0)
	s_barrier
	ds_read_b128 v[194:197], v250
	ds_read_b128 v[198:201], v248
	ds_read_b128 v[202:205], v250 offset:4096
	ds_read_b128 v[206:209], v248 offset:4096
	ds_read_b128 v[162:165], v254
	ds_read_b128 v[166:169], v252
	ds_read_b128 v[170:173], v254 offset:4096
	ds_read_b128 v[174:177], v252 offset:4096
	v_mfma_f32_16x16x32_bf16 v[98:101], v[210:213], v[178:181], v[98:101]
	v_mfma_f32_16x16x32_bf16 v[94:97], v[214:217], v[178:181], v[94:97]
	v_mfma_f32_16x16x32_bf16 v[90:93], v[218:221], v[178:181], v[90:93]
	v_mfma_f32_16x16x32_bf16 v[86:89], v[222:225], v[178:181], v[86:89]
	v_mfma_f32_16x16x32_bf16 v[78:81], v[210:213], v[182:185], v[78:81]
	v_mfma_f32_16x16x32_bf16 v[74:77], v[214:217], v[182:185], v[74:77]
	v_mfma_f32_16x16x32_bf16 v[70:73], v[218:221], v[182:185], v[70:73]
	v_mfma_f32_16x16x32_bf16 v[66:69], v[222:225], v[182:185], v[66:69]
	v_mfma_f32_16x16x32_bf16 v[62:65], v[210:213], v[186:189], v[62:65]
	v_mfma_f32_16x16x32_bf16 v[58:61], v[214:217], v[186:189], v[58:61]
	v_mfma_f32_16x16x32_bf16 v[54:57], v[218:221], v[186:189], v[54:57]
	v_mfma_f32_16x16x32_bf16 v[50:53], v[222:225], v[186:189], v[50:53]
	v_mfma_f32_16x16x32_bf16 v[46:49], v[210:213], v[190:193], v[46:49]
	v_mfma_f32_16x16x32_bf16 v[42:45], v[214:217], v[190:193], v[42:45]
	v_mfma_f32_16x16x32_bf16 v[38:41], v[218:221], v[190:193], v[38:41]
	v_mfma_f32_16x16x32_bf16 v[34:37], v[222:225], v[190:193], v[34:37]
	ds_read_b128 v[186:189], v254 offset:12288
	ds_read_b128 v[182:185], v252 offset:8192
	ds_read_b128 v[178:181], v254 offset:8192
	ds_read_b128 v[190:193], v252 offset:12288
	s_cmp_lt_i32 s40, s35
	s_cselect_b64 s[24:25], -1, 0
	s_cmp_ge_i32 s40, s35
	s_cselect_b64 s[6:7], -1, 0
	s_and_b64 vcc, exec, s[6:7]
	s_waitcnt lgkmcnt(4)
	v_mfma_f32_16x16x32_bf16 v[158:161], v[194:197], v[162:165], v[158:161]
	v_mfma_f32_16x16x32_bf16 v[154:157], v[198:201], v[162:165], v[154:157]
	v_mfma_f32_16x16x32_bf16 v[150:153], v[202:205], v[162:165], v[150:153]
	v_mfma_f32_16x16x32_bf16 v[146:149], v[206:209], v[162:165], v[146:149]
	ds_read_b128 v[162:165], v246
	s_waitcnt lgkmcnt(2)
	v_mfma_f32_16x16x32_bf16 v[142:145], v[194:197], v[166:169], v[142:145]
	v_mfma_f32_16x16x32_bf16 v[138:141], v[198:201], v[166:169], v[138:141]
	v_mfma_f32_16x16x32_bf16 v[134:137], v[202:205], v[166:169], v[134:137]
	v_mfma_f32_16x16x32_bf16 v[130:133], v[206:209], v[166:169], v[130:133]
	s_waitcnt vmcnt(6)
	ds_write_b128 v236, v[26:29]
	ds_write_b128 v236, v[30:33] offset:8192
.LBB0_2217:
	s_lshl_b32 s22, s51, 6
	s_ashr_i32 s23, s22, 31
	s_lshl_b64 s[2:3], s[2:3], 1
	s_add_u32 s2, s29, s2
	s_addc_u32 s3, s30, s3
	s_lshl_b64 s[22:23], s[22:23], 1
	s_add_u32 s26, s2, s22
	s_addc_u32 s27, s3, s23
	global_load_dwordx4 v[30:33], v234, s[26:27]
	global_load_dwordx4 v[26:29], v233, s[26:27]
	s_andn2_b64 vcc, exec, s[24:25]
	ds_read_b128 v[166:169], v244
	v_mfma_f32_16x16x32_bf16 v[126:129], v[194:197], v[170:173], v[126:129]
	v_mfma_f32_16x16x32_bf16 v[122:125], v[198:201], v[170:173], v[122:125]
	v_mfma_f32_16x16x32_bf16 v[118:121], v[202:205], v[170:173], v[118:121]
	v_mfma_f32_16x16x32_bf16 v[114:117], v[206:209], v[170:173], v[114:117]
	ds_read_b128 v[170:173], v246 offset:4096
	v_mfma_f32_16x16x32_bf16 v[110:113], v[194:197], v[174:177], v[110:113]
	v_mfma_f32_16x16x32_bf16 v[106:109], v[198:201], v[174:177], v[106:109]
	v_mfma_f32_16x16x32_bf16 v[102:105], v[202:205], v[174:177], v[102:105]
	v_mfma_f32_16x16x32_bf16 v[82:85], v[206:209], v[174:177], v[82:85]
	ds_read_b128 v[210:213], v242
	ds_read_b128 v[214:217], v237
	ds_read_b128 v[218:221], v242 offset:4096
	ds_read_b128 v[222:225], v237 offset:4096
	ds_read_b128 v[174:177], v244 offset:4096
	s_waitcnt lgkmcnt(10)
	v_mfma_f32_16x16x32_bf16 v[98:101], v[194:197], v[178:181], v[98:101]
	v_mfma_f32_16x16x32_bf16 v[94:97], v[198:201], v[178:181], v[94:97]
	v_mfma_f32_16x16x32_bf16 v[90:93], v[202:205], v[178:181], v[90:93]
	v_mfma_f32_16x16x32_bf16 v[86:89], v[206:209], v[178:181], v[86:89]
	s_waitcnt vmcnt(6)
	ds_write_b128 v236, v[18:21] offset:16384
	ds_write_b128 v236, v[22:25] offset:24576

.LBB0_2221:
	s_lshl_b64 s[20:21], s[20:21], 1
	s_add_u32 s20, s31, s20
	s_addc_u32 s21, s33, s21
	s_add_u32 s20, s20, s22
	s_addc_u32 s21, s21, s23
	global_load_dwordx4 v[14:17], v234, s[20:21]
	global_load_dwordx4 v[10:13], v233, s[20:21]
	s_and_b64 vcc, exec, s[2:3]
	ds_read_b128 v[186:189], v246 offset:12288
	v_mfma_f32_16x16x32_bf16 v[46:49], v[194:197], v[190:193], v[46:49]
	v_mfma_f32_16x16x32_bf16 v[42:45], v[198:201], v[190:193], v[42:45]
	v_mfma_f32_16x16x32_bf16 v[38:41], v[202:205], v[190:193], v[38:41]
	v_mfma_f32_16x16x32_bf16 v[34:37], v[206:209], v[190:193], v[34:37]
	ds_read_b128 v[190:193], v244 offset:12288
	s_waitcnt lgkmcnt(8)
	v_mfma_f32_16x16x32_bf16 v[158:161], v[210:213], v[162:165], v[158:161]
	v_mfma_f32_16x16x32_bf16 v[154:157], v[214:217], v[162:165], v[154:157]
	v_mfma_f32_16x16x32_bf16 v[150:153], v[218:221], v[162:165], v[150:153]
	v_mfma_f32_16x16x32_bf16 v[146:149], v[222:225], v[162:165], v[146:149]
	v_mfma_f32_16x16x32_bf16 v[142:145], v[210:213], v[166:169], v[142:145]
	v_mfma_f32_16x16x32_bf16 v[138:141], v[214:217], v[166:169], v[138:141]
	v_mfma_f32_16x16x32_bf16 v[134:137], v[218:221], v[166:169], v[134:137]
	v_mfma_f32_16x16x32_bf16 v[130:133], v[222:225], v[166:169], v[130:133]
	s_waitcnt vmcnt(6)
	ds_write_b128 v236, v[2:5] offset:49152
	ds_write_b128 v236, v[6:9] offset:57344
.LBB0_2223:
	global_load_dwordx4 v[6:9], v232, s[20:21]
	global_load_dwordx4 v[2:5], v231, s[20:21]
	v_mfma_f32_16x16x32_bf16 v[126:129], v[210:213], v[170:173], v[126:129]
	v_mfma_f32_16x16x32_bf16 v[122:125], v[214:217], v[170:173], v[122:125]
	v_mfma_f32_16x16x32_bf16 v[118:121], v[218:221], v[170:173], v[118:121]
	v_mfma_f32_16x16x32_bf16 v[114:117], v[222:225], v[170:173], v[114:117]
	v_mfma_f32_16x16x32_bf16 v[110:113], v[210:213], v[174:177], v[110:113]
	v_mfma_f32_16x16x32_bf16 v[106:109], v[214:217], v[174:177], v[106:109]
	v_mfma_f32_16x16x32_bf16 v[102:105], v[218:221], v[174:177], v[102:105]
	v_mfma_f32_16x16x32_bf16 v[82:85], v[222:225], v[174:177], v[82:85]
	s_add_i32 s26, s51, 1
	s_cmp_lg_u32 s26, 16
	s_cbranch_scc1 .LBB0_2227
	s_add_i32 s28, s28, s11
	s_cmp_gt_i32 s28, 31
	s_cbranch_scc1 .LBB0_2226
	s_ashr_i32 s3, s28, 31
	s_lshr_b32 s3, s3, 27
	s_add_i32 s3, s28, s3
	s_ashr_i32 s3, s3, 5
	s_mov_b32 s2, s10
	s_lshl_b32 s20, s3, 6
	s_lshl_b32 s21, s28, 1
	s_sub_i32 s20, s21, s20
	s_and_b32 s2, s2, 7
	s_and_b32 s20, s20, -8
	s_lshl_b32 s3, s3, 2
	s_and_b32 s21, s28, 3
	s_or_b32 s48, s3, s21
	s_or_b32 s49, s2, s20

.Lnodef_J1_9:
	ds_read_b128 v[186:189], v255 offset:12288
	ds_read_b128 v[182:185], v253 offset:8192
	ds_read_b128 v[178:181], v255 offset:8192
	ds_read_b128 v[190:193], v253 offset:12288
	s_add_i32 s0, s30, -1
	s_cmp_lt_i32 s0, s33
	s_cselect_b64 s[14:15], -1, 0
	s_cmp_ge_i32 s0, s33
	s_waitcnt lgkmcnt(4)
	v_mfma_f32_16x16x32_bf16 v[158:161], v[194:197], v[162:165], v[158:161]
	v_mfma_f32_16x16x32_bf16 v[154:157], v[198:201], v[162:165], v[154:157]
	v_mfma_f32_16x16x32_bf16 v[150:153], v[202:205], v[162:165], v[150:153]
	v_mfma_f32_16x16x32_bf16 v[146:149], v[206:209], v[162:165], v[146:149]
	ds_read_b128 v[162:165], v247
	s_waitcnt lgkmcnt(2)
	v_mfma_f32_16x16x32_bf16 v[142:145], v[194:197], v[166:169], v[142:145]
	v_mfma_f32_16x16x32_bf16 v[138:141], v[198:201], v[166:169], v[138:141]
	v_mfma_f32_16x16x32_bf16 v[134:137], v[202:205], v[166:169], v[134:137]
	v_mfma_f32_16x16x32_bf16 v[130:133], v[206:209], v[166:169], v[130:133]
	s_waitcnt vmcnt(6)
	ds_write_b128 v235, v[30:33]
	ds_write_b128 v235, v[26:29] offset:8192
.LBB0_2547:
	s_lshl_b32 s0, s41, 8
	s_mul_i32 s12, s41, 0xb0000
	s_mul_hi_i32 s13, s0, 0xb00
	s_lshl_b32 s0, s18, 6
	s_ashr_i32 s1, s0, 31
	s_lshl_b64 s[6:7], s[12:13], 1
	s_add_u32 s16, s21, s6
	s_addc_u32 s17, s22, s7
	s_lshl_b64 s[6:7], s[0:1], 1
	s_add_u32 s16, s16, s6
	s_addc_u32 s17, s17, s7
	global_load_dwordx4 v[26:29], v234, s[16:17]
	global_load_dwordx4 v[30:33], v233, s[16:17]
	s_andn2_b64 vcc, exec, s[14:15]
	ds_read_b128 v[166:169], v245
	v_mfma_f32_16x16x32_bf16 v[126:129], v[194:197], v[170:173], v[126:129]
	v_mfma_f32_16x16x32_bf16 v[122:125], v[198:201], v[170:173], v[122:125]
	v_mfma_f32_16x16x32_bf16 v[118:121], v[202:205], v[170:173], v[118:121]
	v_mfma_f32_16x16x32_bf16 v[114:117], v[206:209], v[170:173], v[114:117]
	ds_read_b128 v[170:173], v247 offset:4096
	v_mfma_f32_16x16x32_bf16 v[110:113], v[194:197], v[174:177], v[110:113]
	v_mfma_f32_16x16x32_bf16 v[106:109], v[198:201], v[174:177], v[106:109]
	v_mfma_f32_16x16x32_bf16 v[102:105], v[202:205], v[174:177], v[102:105]
	v_mfma_f32_16x16x32_bf16 v[82:85], v[206:209], v[174:177], v[82:85]
	ds_read_b128 v[210:213], v243
	ds_read_b128 v[214:217], v241
	ds_read_b128 v[218:221], v243 offset:4096
	ds_read_b128 v[222:225], v241 offset:4096
	ds_read_b128 v[174:177], v245 offset:4096
	s_waitcnt lgkmcnt(10)
	v_mfma_f32_16x16x32_bf16 v[98:101], v[194:197], v[178:181], v[98:101]
	v_mfma_f32_16x16x32_bf16 v[94:97], v[198:201], v[178:181], v[94:97]
	v_mfma_f32_16x16x32_bf16 v[90:93], v[202:205], v[178:181], v[90:93]
	v_mfma_f32_16x16x32_bf16 v[86:89], v[206:209], v[178:181], v[86:89]
	s_waitcnt vmcnt(6)
	ds_write_b128 v235, v[22:25] offset:16384
	ds_write_b128 v235, v[18:21] offset:24576
.LBB0_2549:
	global_load_dwordx4 v[18:21], v232, s[16:17]
	global_load_dwordx4 v[22:25], v231, s[16:17]
	s_and_b64 vcc, exec, s[0:1]
	ds_read_b128 v[178:181], v247 offset:8192
	s_waitcnt lgkmcnt(4)
	v_mfma_f32_16x16x32_bf16 v[78:81], v[194:197], v[182:185], v[78:81]
	v_mfma_f32_16x16x32_bf16 v[74:77], v[198:201], v[182:185], v[74:77]
	v_mfma_f32_16x16x32_bf16 v[70:73], v[202:205], v[182:185], v[70:73]
	v_mfma_f32_16x16x32_bf16 v[66:69], v[206:209], v[182:185], v[66:69]
	ds_read_b128 v[182:185], v245 offset:8192
	v_mfma_f32_16x16x32_bf16 v[62:65], v[194:197], v[186:189], v[62:65]
	v_mfma_f32_16x16x32_bf16 v[58:61], v[198:201], v[186:189], v[58:61]
	v_mfma_f32_16x16x32_bf16 v[54:57], v[202:205], v[186:189], v[54:57]
	v_mfma_f32_16x16x32_bf16 v[50:53], v[206:209], v[186:189], v[50:53]
	s_waitcnt vmcnt(6)
	ds_write_b128 v235, v[14:17] offset:32768
	ds_write_b128 v235, v[10:13] offset:40960
.LBB0_2551:
	s_lshl_b32 s15, s40, 8
	s_mul_i32 s14, s40, 0xb0000
	s_mul_hi_i32 s15, s15, 0xb00
	s_lshl_b64 s[16:17], s[14:15], 1
	s_add_u32 s16, s23, s16
	s_addc_u32 s17, s24, s17
	s_add_u32 s6, s16, s6
	s_addc_u32 s7, s17, s7
	global_load_dwordx4 v[10:13], v234, s[6:7]
	global_load_dwordx4 v[14:17], v233, s[6:7]
	s_and_b64 vcc, exec, s[0:1]
	ds_read_b128 v[186:189], v247 offset:12288
	v_mfma_f32_16x16x32_bf16 v[46:49], v[194:197], v[190:193], v[46:49]
	v_mfma_f32_16x16x32_bf16 v[42:45], v[198:201], v[190:193], v[42:45]
	v_mfma_f32_16x16x32_bf16 v[38:41], v[202:205], v[190:193], v[38:41]
	v_mfma_f32_16x16x32_bf16 v[34:37], v[206:209], v[190:193], v[34:37]
	ds_read_b128 v[190:193], v245 offset:12288
	s_waitcnt lgkmcnt(8)
	v_mfma_f32_16x16x32_bf16 v[158:161], v[210:213], v[162:165], v[158:161]
	v_mfma_f32_16x16x32_bf16 v[154:157], v[214:217], v[162:165], v[154:157]
	v_mfma_f32_16x16x32_bf16 v[150:153], v[218:221], v[162:165], v[150:153]
	v_mfma_f32_16x16x32_bf16 v[146:149], v[222:225], v[162:165], v[146:149]
	v_mfma_f32_16x16x32_bf16 v[142:145], v[210:213], v[166:169], v[142:145]
	v_mfma_f32_16x16x32_bf16 v[138:141], v[214:217], v[166:169], v[138:141]
	v_mfma_f32_16x16x32_bf16 v[134:137], v[218:221], v[166:169], v[134:137]
	v_mfma_f32_16x16x32_bf16 v[130:133], v[222:225], v[166:169], v[130:133]
	s_waitcnt vmcnt(6)
	ds_write_b128 v235, v[6:9] offset:49152
	ds_write_b128 v235, v[2:5] offset:57344
.LBB0_2553:
	global_load_dwordx4 v[2:5], v232, s[6:7]
	global_load_dwordx4 v[6:9], v231, s[6:7]
	v_mfma_f32_16x16x32_bf16 v[126:129], v[210:213], v[170:173], v[126:129]
	v_mfma_f32_16x16x32_bf16 v[122:125], v[214:217], v[170:173], v[122:125]
	v_mfma_f32_16x16x32_bf16 v[118:121], v[218:221], v[170:173], v[118:121]
	v_mfma_f32_16x16x32_bf16 v[114:117], v[222:225], v[170:173], v[114:117]
	v_mfma_f32_16x16x32_bf16 v[110:113], v[210:213], v[174:177], v[110:113]
	v_mfma_f32_16x16x32_bf16 v[106:109], v[214:217], v[174:177], v[106:109]
	v_mfma_f32_16x16x32_bf16 v[102:105], v[218:221], v[174:177], v[102:105]
	v_mfma_f32_16x16x32_bf16 v[82:85], v[222:225], v[174:177], v[82:85]
	s_add_i32 s43, s18, 1
	s_cmp_lg_u32 s43, 44
	s_cbranch_scc1 .LBB0_2557
	s_add_i32 s20, s20, s11
	s_cmp_gt_i32 s20, 31
	s_cbranch_scc1 .LBB0_2556
	s_ashr_i32 s1, s20, 31
	s_lshr_b32 s1, s1, 27
	s_add_i32 s1, s20, s1
	s_ashr_i32 s1, s1, 5
	s_mov_b32 s0, s10
	s_lshl_b32 s6, s1, 6
	s_lshl_b32 s7, s20, 1
	s_sub_i32 s6, s7, s6
	s_and_b32 s0, s0, 7
	s_and_b32 s6, s6, -8
	s_lshl_b32 s1, s1, 2
	s_and_b32 s7, s20, 3
	s_or_b32 s41, s0, s6
	s_or_b32 s40, s1, s7
	s_lshl_b32 s0, s41, 8
	s_mul_hi_i32 s13, s0, 0xb00
	s_lshl_b32 s0, s40, 8
	s_mul_i32 s12, s41, 0xb0000
	s_mul_i32 s14, s40, 0xb0000
	s_mul_hi_i32 s15, s0, 0xb00

.LBB0_2557:
	s_waitcnt lgkmcnt(0)
	s_barrier
	ds_read_b128 v[194:197], v250
	ds_read_b128 v[198:201], v248
	ds_read_b128 v[202:205], v250 offset:4096
	ds_read_b128 v[206:209], v248 offset:4096
	ds_read_b128 v[162:165], v254
	ds_read_b128 v[166:169], v252
	ds_read_b128 v[170:173], v254 offset:4096
	ds_read_b128 v[174:177], v252 offset:4096
	v_mfma_f32_16x16x32_bf16 v[98:101], v[210:213], v[178:181], v[98:101]
	v_mfma_f32_16x16x32_bf16 v[94:97], v[214:217], v[178:181], v[94:97]
	v_mfma_f32_16x16x32_bf16 v[90:93], v[218:221], v[178:181], v[90:93]
	v_mfma_f32_16x16x32_bf16 v[86:89], v[222:225], v[178:181], v[86:89]
	v_mfma_f32_16x16x32_bf16 v[78:81], v[210:213], v[182:185], v[78:81]
	v_mfma_f32_16x16x32_bf16 v[74:77], v[214:217], v[182:185], v[74:77]
	v_mfma_f32_16x16x32_bf16 v[70:73], v[218:221], v[182:185], v[70:73]
	v_mfma_f32_16x16x32_bf16 v[66:69], v[222:225], v[182:185], v[66:69]
	v_mfma_f32_16x16x32_bf16 v[62:65], v[210:213], v[186:189], v[62:65]
	v_mfma_f32_16x16x32_bf16 v[58:61], v[214:217], v[186:189], v[58:61]
	v_mfma_f32_16x16x32_bf16 v[54:57], v[218:221], v[186:189], v[54:57]
	v_mfma_f32_16x16x32_bf16 v[50:53], v[222:225], v[186:189], v[50:53]
	v_mfma_f32_16x16x32_bf16 v[46:49], v[210:213], v[190:193], v[46:49]
	v_mfma_f32_16x16x32_bf16 v[42:45], v[214:217], v[190:193], v[42:45]
	v_mfma_f32_16x16x32_bf16 v[38:41], v[218:221], v[190:193], v[38:41]
	v_mfma_f32_16x16x32_bf16 v[34:37], v[222:225], v[190:193], v[34:37]
	ds_read_b128 v[186:189], v254 offset:12288
	ds_read_b128 v[182:185], v252 offset:8192
	ds_read_b128 v[178:181], v254 offset:8192
	ds_read_b128 v[190:193], v252 offset:12288
	s_cmp_lt_i32 s30, s33
	s_cselect_b64 s[16:17], -1, 0
	s_cmp_ge_i32 s30, s33
	s_cselect_b64 s[6:7], -1, 0
	s_and_b64 vcc, exec, s[6:7]
	s_waitcnt lgkmcnt(4)
	v_mfma_f32_16x16x32_bf16 v[158:161], v[194:197], v[162:165], v[158:161]
	v_mfma_f32_16x16x32_bf16 v[154:157], v[198:201], v[162:165], v[154:157]
	v_mfma_f32_16x16x32_bf16 v[150:153], v[202:205], v[162:165], v[150:153]
	v_mfma_f32_16x16x32_bf16 v[146:149], v[206:209], v[162:165], v[146:149]
	ds_read_b128 v[162:165], v246
	s_waitcnt lgkmcnt(2)
	v_mfma_f32_16x16x32_bf16 v[142:145], v[194:197], v[166:169], v[142:145]
	v_mfma_f32_16x16x32_bf16 v[138:141], v[198:201], v[166:169], v[138:141]
	v_mfma_f32_16x16x32_bf16 v[134:137], v[202:205], v[166:169], v[134:137]
	v_mfma_f32_16x16x32_bf16 v[130:133], v[206:209], v[166:169], v[130:133]
	s_waitcnt vmcnt(6)
	ds_write_b128 v236, v[26:29]
	ds_write_b128 v236, v[30:33] offset:8192
.LBB0_2559:
	s_lshl_b32 s0, s43, 6
	s_ashr_i32 s1, s0, 31
	s_lshl_b64 s[12:13], s[12:13], 1
	s_add_u32 s18, s21, s12
	s_addc_u32 s19, s22, s13
	s_lshl_b64 s[12:13], s[0:1], 1
	s_add_u32 s18, s18, s12
	s_addc_u32 s19, s19, s13
	global_load_dwordx4 v[30:33], v234, s[18:19]
	global_load_dwordx4 v[26:29], v233, s[18:19]
	s_andn2_b64 vcc, exec, s[16:17]
	ds_read_b128 v[166:169], v244
	v_mfma_f32_16x16x32_bf16 v[126:129], v[194:197], v[170:173], v[126:129]
	v_mfma_f32_16x16x32_bf16 v[122:125], v[198:201], v[170:173], v[122:125]
	v_mfma_f32_16x16x32_bf16 v[118:121], v[202:205], v[170:173], v[118:121]
	v_mfma_f32_16x16x32_bf16 v[114:117], v[206:209], v[170:173], v[114:117]
	ds_read_b128 v[170:173], v246 offset:4096
	v_mfma_f32_16x16x32_bf16 v[110:113], v[194:197], v[174:177], v[110:113]
	v_mfma_f32_16x16x32_bf16 v[106:109], v[198:201], v[174:177], v[106:109]
	v_mfma_f32_16x16x32_bf16 v[102:105], v[202:205], v[174:177], v[102:105]
	v_mfma_f32_16x16x32_bf16 v[82:85], v[206:209], v[174:177], v[82:85]
	ds_read_b128 v[210:213], v242
	ds_read_b128 v[214:217], v237
	ds_read_b128 v[218:221], v242 offset:4096
	ds_read_b128 v[222:225], v237 offset:4096
	ds_read_b128 v[174:177], v244 offset:4096
	s_waitcnt lgkmcnt(10)
	v_mfma_f32_16x16x32_bf16 v[98:101], v[194:197], v[178:181], v[98:101]
	v_mfma_f32_16x16x32_bf16 v[94:97], v[198:201], v[178:181], v[94:97]
	v_mfma_f32_16x16x32_bf16 v[90:93], v[202:205], v[178:181], v[90:93]
	v_mfma_f32_16x16x32_bf16 v[86:89], v[206:209], v[178:181], v[86:89]
	s_waitcnt vmcnt(6)
	ds_write_b128 v236, v[18:21] offset:16384
	ds_write_b128 v236, v[22:25] offset:24576
.LBB0_2561:
	global_load_dwordx4 v[22:25], v232, s[18:19]
	global_load_dwordx4 v[18:21], v231, s[18:19]
	s_and_b64 vcc, exec, s[0:1]
	ds_read_b128 v[178:181], v246 offset:8192
	s_waitcnt lgkmcnt(4)
	v_mfma_f32_16x16x32_bf16 v[78:81], v[194:197], v[182:185], v[78:81]
	v_mfma_f32_16x16x32_bf16 v[74:77], v[198:201], v[182:185], v[74:77]
	v_mfma_f32_16x16x32_bf16 v[70:73], v[202:205], v[182:185], v[70:73]
	v_mfma_f32_16x16x32_bf16 v[66:69], v[206:209], v[182:185], v[66:69]
	ds_read_b128 v[182:185], v244 offset:8192
	v_mfma_f32_16x16x32_bf16 v[62:65], v[194:197], v[186:189], v[62:65]
	v_mfma_f32_16x16x32_bf16 v[58:61], v[198:201], v[186:189], v[58:61]
	v_mfma_f32_16x16x32_bf16 v[54:57], v[202:205], v[186:189], v[54:57]
	v_mfma_f32_16x16x32_bf16 v[50:53], v[206:209], v[186:189], v[50:53]
	s_waitcnt vmcnt(6)
	ds_write_b128 v236, v[10:13] offset:32768
	ds_write_b128 v236, v[14:17] offset:40960
.LBB0_2563:
	s_lshl_b64 s[14:15], s[14:15], 1
	s_add_u32 s14, s23, s14
	s_addc_u32 s15, s24, s15
	s_add_u32 s12, s14, s12
	s_addc_u32 s13, s15, s13
	global_load_dwordx4 v[14:17], v234, s[12:13]
	global_load_dwordx4 v[10:13], v233, s[12:13]
	s_and_b64 vcc, exec, s[0:1]
	ds_read_b128 v[186:189], v246 offset:12288
	v_mfma_f32_16x16x32_bf16 v[46:49], v[194:197], v[190:193], v[46:49]
	v_mfma_f32_16x16x32_bf16 v[42:45], v[198:201], v[190:193], v[42:45]
	v_mfma_f32_16x16x32_bf16 v[38:41], v[202:205], v[190:193], v[38:41]
	v_mfma_f32_16x16x32_bf16 v[34:37], v[206:209], v[190:193], v[34:37]
	ds_read_b128 v[190:193], v244 offset:12288
	s_waitcnt lgkmcnt(8)
	v_mfma_f32_16x16x32_bf16 v[158:161], v[210:213], v[162:165], v[158:161]
	v_mfma_f32_16x16x32_bf16 v[154:157], v[214:217], v[162:165], v[154:157]
	v_mfma_f32_16x16x32_bf16 v[150:153], v[218:221], v[162:165], v[150:153]
	v_mfma_f32_16x16x32_bf16 v[146:149], v[222:225], v[162:165], v[146:149]
	v_mfma_f32_16x16x32_bf16 v[142:145], v[210:213], v[166:169], v[142:145]
	v_mfma_f32_16x16x32_bf16 v[138:141], v[214:217], v[166:169], v[138:141]
	v_mfma_f32_16x16x32_bf16 v[134:137], v[218:221], v[166:169], v[134:137]
	v_mfma_f32_16x16x32_bf16 v[130:133], v[222:225], v[166:169], v[130:133]
	s_waitcnt vmcnt(6)
	ds_write_b128 v236, v[2:5] offset:49152
	ds_write_b128 v236, v[6:9] offset:57344
.LBB0_2565:
	global_load_dwordx4 v[6:9], v232, s[12:13]
	global_load_dwordx4 v[2:5], v231, s[12:13]
	v_mfma_f32_16x16x32_bf16 v[126:129], v[210:213], v[170:173], v[126:129]
	v_mfma_f32_16x16x32_bf16 v[122:125], v[214:217], v[170:173], v[122:125]
	v_mfma_f32_16x16x32_bf16 v[118:121], v[218:221], v[170:173], v[118:121]
	v_mfma_f32_16x16x32_bf16 v[114:117], v[222:225], v[170:173], v[114:117]
	v_mfma_f32_16x16x32_bf16 v[110:113], v[210:213], v[174:177], v[110:113]
	v_mfma_f32_16x16x32_bf16 v[106:109], v[214:217], v[174:177], v[106:109]
	v_mfma_f32_16x16x32_bf16 v[102:105], v[218:221], v[174:177], v[102:105]
	v_mfma_f32_16x16x32_bf16 v[82:85], v[222:225], v[174:177], v[82:85]
	s_add_i32 s18, s43, 1
	s_cmp_lg_u32 s18, 44
	s_cbranch_scc1 .LBB0_2569
	s_add_i32 s20, s20, s11
	s_cmp_gt_i32 s20, 31
	s_cbranch_scc1 .LBB0_2568
	s_ashr_i32 s1, s20, 31
	s_lshr_b32 s1, s1, 27
	s_add_i32 s1, s20, s1
	s_ashr_i32 s1, s1, 5
	s_mov_b32 s0, s10
	s_lshl_b32 s12, s1, 6
	s_lshl_b32 s13, s20, 1
	s_sub_i32 s12, s13, s12
	s_and_b32 s0, s0, 7
	s_and_b32 s12, s12, -8
	s_lshl_b32 s1, s1, 2
	s_and_b32 s13, s20, 3
	s_or_b32 s40, s1, s13
	s_or_b32 s41, s0, s12
